# nt (streaming) cache policy on once-read loads: f32 weight reads in all three conversion loops, x rows in RMSNorm, attention/SSD recurrent state in the sample units
# speedup vs baseline: 1.0059x; 1.0035x over previous
; #define LAS __attribute__((address_space(3)))
; __device__ __forceinline__ void p0_transpose_item(const float* W, int K, int N, bf16* WT, int mode, LAS float* scr, int item, int lane, const float* kscale = nullptr) {
;     const int nblk = N / 32, kb = item / nblk, nb = item % nblk, k0 = 64 * kb, n0 = 32 * nb;
;     const int rb = (mode == 0 || mode == 3 || mode == 4) ? n0 : ((n0 >> 7) * 256 + (n0 & 127) + (mode == 2 ? 128 : 0));
;     float wv[32];
; #pragma unroll
;     for (int i = 0; i < 32; ++i) wv[i] = W[(size_t)(k0 + 2 * i + (lane >> 5)) * N + n0 + (lane & 31)];
; #pragma unroll
;     for (int i = 0; i < 32; ++i) scr[(2 * i + (lane >> 5)) * 33 + (lane & 31)] = wv[i];
; template <int WHICH> __device__ __forceinline__ void convert_weights(const Frame& F, int gw, int ngw) {
;     ...
;     for (int it = gw; it < NIT; it += ngw) {
;         if (WHICH == 0) { if (it < I_1) p0_transpose_item(P_w_in, DM, 9248, P_W1, 0, scr, it, F.lane); else p0_transpose_item(P_w_out, DM, DM, P_W2, 4, scr, it - I_1, F.lane); }
.LBB0_9:
	s_cmpk_gt_i32 s53, 0x483f
	s_mov_b64 s[12:13], -1
	s_cbranch_scc0 .LBB0_11
	s_load_dwordx2 s[14:15], s[0:1], 0x98
	s_add_i32 s12, s53, 0xffffb7c0
	s_lshr_b32 s13, s12, 1
	s_add_i32 s12, s9, 0xfff6f800
	s_and_b32 s54, s13, 0x7fc0
	s_and_b32 s12, s12, 0xfe0
	v_or_b32_e32 v21, s54, v1
	s_lshl_b32 s54, s12, 2
	s_waitcnt lgkmcnt(0)
	s_add_u32 s14, s14, s54
	s_addc_u32 s15, s15, 0
	v_lshl_add_u64 v[22:23], s[14:15], 0, v[2:3]
	v_lshlrev_b32_e32 v24, 14, v21
	v_mov_b32_e32 v25, v3
	v_lshl_add_u64 v[22:23], v[22:23], 0, v[24:25]
	v_add_co_u32_e32 v24, vcc, s16, v22
	s_and_b32 s13, s13, 0xfc0
	s_nop 0
	v_addc_co_u32_e32 v25, vcc, 0, v23, vcc
	v_add_co_u32_e32 v26, vcc, s17, v22
	s_nop 1
	v_addc_co_u32_e32 v27, vcc, 0, v23, vcc
	v_add_co_u32_e32 v28, vcc, s18, v22
	s_nop 1
	v_addc_co_u32_e32 v29, vcc, 0, v23, vcc
	v_add_co_u32_e32 v30, vcc, s19, v22
	s_nop 1
	v_addc_co_u32_e32 v31, vcc, 0, v23, vcc
	v_add_co_u32_e32 v32, vcc, s20, v22
	s_nop 1
	v_addc_co_u32_e32 v33, vcc, 0, v23, vcc
	v_add_co_u32_e32 v34, vcc, s21, v22
	s_nop 1
	v_addc_co_u32_e32 v35, vcc, 0, v23, vcc
	v_add_co_u32_e32 v36, vcc, s22, v22
	s_nop 1
	v_addc_co_u32_e32 v37, vcc, 0, v23, vcc
	global_load_dword v21, v[22:23], off nt
	global_load_dword v40, v[24:25], off nt
	global_load_dword v41, v[26:27], off nt
	global_load_dword v42, v[28:29], off nt
	global_load_dword v43, v[30:31], off nt
	global_load_dword v44, v[32:33], off nt
	global_load_dword v45, v[34:35], off nt
	global_load_dword v46, v[36:37], off nt
	v_add_co_u32_e32 v24, vcc, s23, v22
	s_nop 1
	v_addc_co_u32_e32 v25, vcc, 0, v23, vcc
	v_add_co_u32_e32 v26, vcc, s24, v22
	s_nop 1
	v_addc_co_u32_e32 v27, vcc, 0, v23, vcc
	v_add_co_u32_e32 v28, vcc, s25, v22
	s_nop 1
	v_addc_co_u32_e32 v29, vcc, 0, v23, vcc
	v_add_co_u32_e32 v30, vcc, s26, v22
	s_nop 1
	v_addc_co_u32_e32 v31, vcc, 0, v23, vcc
	v_add_co_u32_e32 v32, vcc, s27, v22
	s_nop 1
	v_addc_co_u32_e32 v33, vcc, 0, v23, vcc
	v_add_co_u32_e32 v34, vcc, s28, v22
	s_nop 1
	v_addc_co_u32_e32 v35, vcc, 0, v23, vcc
	v_add_co_u32_e32 v36, vcc, s29, v22
	s_nop 1
	v_addc_co_u32_e32 v37, vcc, 0, v23, vcc
	v_add_co_u32_e32 v38, vcc, s30, v22
	s_nop 1
	v_addc_co_u32_e32 v39, vcc, 0, v23, vcc
	global_load_dword v47, v[24:25], off nt
	global_load_dword v48, v[26:27], off nt
	global_load_dword v49, v[28:29], off nt
	global_load_dword v50, v[30:31], off nt
	global_load_dword v51, v[32:33], off nt
	global_load_dword v52, v[34:35], off nt
	global_load_dword v53, v[36:37], off nt
	global_load_dword v54, v[38:39], off nt
	v_add_co_u32_e32 v24, vcc, s31, v22
	s_nop 1
	v_addc_co_u32_e32 v25, vcc, 0, v23, vcc
	v_add_co_u32_e32 v26, vcc, s33, v22
	s_nop 1
	v_addc_co_u32_e32 v27, vcc, 0, v23, vcc
	v_add_co_u32_e32 v28, vcc, s34, v22
	s_nop 1
	v_addc_co_u32_e32 v29, vcc, 0, v23, vcc
	v_add_co_u32_e32 v30, vcc, s35, v22
	s_nop 1
	v_addc_co_u32_e32 v31, vcc, 0, v23, vcc
	v_add_co_u32_e32 v32, vcc, s36, v22
	s_nop 1
	v_addc_co_u32_e32 v33, vcc, 0, v23, vcc
	v_add_co_u32_e32 v34, vcc, s37, v22
	s_nop 1
	v_addc_co_u32_e32 v35, vcc, 0, v23, vcc
	v_add_co_u32_e32 v36, vcc, s38, v22
	s_nop 1
	v_addc_co_u32_e32 v37, vcc, 0, v23, vcc
	v_add_co_u32_e32 v38, vcc, s39, v22
	s_nop 1
	v_addc_co_u32_e32 v39, vcc, 0, v23, vcc
	global_load_dword v55, v[24:25], off nt
	global_load_dword v56, v[26:27], off nt
	global_load_dword v57, v[28:29], off nt
	global_load_dword v58, v[30:31], off nt
	global_load_dword v59, v[32:33], off nt
	global_load_dword v60, v[34:35], off nt
	global_load_dword v61, v[36:37], off nt
	s_nop 0
	global_load_dword v38, v[38:39], off nt
	v_add_co_u32_e32 v24, vcc, s40, v22
	s_nop 1
	v_addc_co_u32_e32 v25, vcc, 0, v23, vcc
	v_add_co_u32_e32 v26, vcc, s41, v22
	s_nop 1
	v_addc_co_u32_e32 v27, vcc, 0, v23, vcc
	v_add_co_u32_e32 v28, vcc, s42, v22
	s_nop 1
	v_addc_co_u32_e32 v29, vcc, 0, v23, vcc
	v_add_co_u32_e32 v30, vcc, s43, v22
	s_nop 1
	v_addc_co_u32_e32 v31, vcc, 0, v23, vcc
	v_add_co_u32_e32 v32, vcc, s44, v22
	s_nop 1
	v_addc_co_u32_e32 v33, vcc, 0, v23, vcc
	v_add_co_u32_e32 v34, vcc, s45, v22
	s_nop 1
	v_addc_co_u32_e32 v35, vcc, 0, v23, vcc
	v_add_co_u32_e32 v36, vcc, s46, v22
	s_nop 1
	v_addc_co_u32_e32 v37, vcc, 0, v23, vcc
	v_add_co_u32_e32 v22, vcc, s47, v22
	s_nop 1
	v_addc_co_u32_e32 v23, vcc, 0, v23, vcc
	global_load_dword v24, v[24:25], off nt
	s_nop 0
	global_load_dword v25, v[26:27], off nt
	s_nop 0
	global_load_dword v26, v[28:29], off nt
	global_load_dword v27, v[30:31], off nt
	s_nop 0
	global_load_dword v28, v[32:33], off nt
	global_load_dword v29, v[34:35], off nt
	global_load_dword v30, v[36:37], off nt
	s_nop 0
	global_load_dword v22, v[22:23], off nt
	s_waitcnt vmcnt(30)
; #define LAS __attribute__((address_space(3)))
; #define LDS_WAIT() asm volatile("s_waitcnt lgkmcnt(0)" ::: "memory")
; __device__ __forceinline__ unsigned cvtpk(float lo, float hi) { f32x2_t v = {lo, hi}; bf16x2_t b = __builtin_convertvector(v, bf16x2_t); return __builtin_bit_cast(unsigned, b); }
; __device__ __forceinline__ void p0_transpose_item(const float* W, int K, int N, bf16* WT, int mode, LAS float* scr, int item, int lane, const float* kscale = nullptr) {
;     ...
;     for (int i = 0; i < 32; ++i) scr[(2 * i + (lane >> 5)) * 33 + (lane & 31)] = wv[i];
;     LDS_WAIT(); asm volatile("" ::: "memory");
;     const int c = lane & 7;
;     f32x4 ks0 = (f32x4){1.f, 1.f, 1.f, 1.f}, ks1 = ks0; if (kscale) { ks0 = *(const f32x4*)(kscale + k0 + 8 * c); ks1 = *(const f32x4*)(kscale + k0 + 8 * c + 4); }
; #pragma unroll
;     for (int j = 0; j < 4; ++j) { const int n = (lane >> 3) + 8 * j; const LAS float* s = scr + (8 * c) * 33 + n;
;         u32x4 o; o.x = cvtpk(s[0 * 33] * ks0.x, s[1 * 33] * ks0.y); o.y = cvtpk(s[2 * 33] * ks0.z, s[3 * 33] * ks0.w); o.z = cvtpk(s[4 * 33] * ks1.x, s[5 * 33] * ks1.y); o.w = cvtpk(s[6 * 33] * ks1.z, s[7 * 33] * ks1.w);
;         const int k0d = (mode == 4) ? ((k0 + 2048) & 4095) : k0;
;         const size_t dst = (mode == 3) ? ((size_t)(((rb + n) >> 8) * (K >> 6) + kb) * 256 + ((rb + n) & 255)) * 64 + 8 * c : (size_t)(rb + n) * K + k0d + 8 * c;
;         *(u32x4*)(WT + dst) = o; }
;     LDS_WAIT(); asm volatile("" ::: "memory");
	ds_write2_b32 v12, v21, v40 offset1:66
	s_waitcnt vmcnt(28)
	ds_write2_b32 v12, v41, v42 offset0:132 offset1:198
	s_waitcnt vmcnt(26)
	ds_write2_b32 v13, v43, v44 offset0:8 offset1:74
	s_waitcnt vmcnt(24)
	ds_write2_b32 v13, v45, v46 offset0:140 offset1:206
	s_waitcnt vmcnt(22)
	ds_write2_b32 v14, v47, v48 offset0:16 offset1:82
	s_waitcnt vmcnt(20)
	ds_write2_b32 v14, v49, v50 offset0:148 offset1:214
	s_waitcnt vmcnt(18)
	ds_write2_b32 v15, v51, v52 offset0:24 offset1:90
	s_waitcnt vmcnt(16)
	ds_write2_b32 v15, v53, v54 offset0:156 offset1:222
	s_waitcnt vmcnt(14)
	ds_write2_b32 v16, v55, v56 offset0:32 offset1:98
	s_waitcnt vmcnt(12)
	ds_write2_b32 v16, v57, v58 offset0:164 offset1:230
	s_waitcnt vmcnt(10)
	ds_write2_b32 v17, v59, v60 offset0:40 offset1:106
	s_waitcnt vmcnt(8)
	ds_write2_b32 v17, v61, v38 offset0:172 offset1:238
	s_waitcnt vmcnt(6)
	ds_write2_b32 v18, v24, v25 offset0:48 offset1:114
	s_waitcnt vmcnt(4)
	ds_write2_b32 v18, v26, v27 offset0:180 offset1:246
	s_waitcnt vmcnt(2)
	ds_write2_b32 v19, v28, v29 offset0:56 offset1:122
	s_waitcnt vmcnt(0)
	ds_write2_b32 v19, v30, v22 offset0:188 offset1:254
	s_waitcnt lgkmcnt(0)
	ds_read2_b32 v[26:27], v8 offset0:33 offset1:41
	ds_read2_b32 v[28:29], v8 offset1:8
	ds_read2_b32 v[30:31], v8 offset0:66 offset1:74
	ds_read2_b32 v[32:33], v8 offset0:99 offset1:107
	ds_read2_b32 v[34:35], v8 offset0:132 offset1:140
	ds_read2_b32 v[36:37], v8 offset0:165 offset1:173
	ds_read2_b32 v[38:39], v8 offset0:198 offset1:206
	ds_read2_b32 v[40:41], v8 offset0:231 offset1:239
	s_waitcnt lgkmcnt(6)
	v_cvt_pk_bf16_f32 v22, v28, v26
	v_or_b32_e32 v26, s12, v7
	v_bitop3_b32 v21, s13, v20, v6 bitop3:0x36
	v_lshlrev_b32_e32 v42, 13, v26
	v_mov_b32_e32 v43, v3
	v_lshl_add_u64 v[42:43], s[4:5], 0, v[42:43]
	v_lshlrev_b32_e32 v44, 1, v21
	v_mov_b32_e32 v45, v3
	s_waitcnt lgkmcnt(4)
	v_cvt_pk_bf16_f32 v23, v30, v32
	s_waitcnt lgkmcnt(2)
	v_cvt_pk_bf16_f32 v24, v34, v36
	s_waitcnt lgkmcnt(0)
	v_cvt_pk_bf16_f32 v25, v38, v40
	v_lshl_add_u64 v[42:43], v[42:43], 0, v[44:45]
	global_store_dwordx4 v[42:43], v[22:25], off
	v_or_b32_e32 v21, s12, v9
	v_lshlrev_b32_e32 v26, 13, v21
	v_cvt_pk_bf16_f32 v22, v29, v27
	v_cvt_pk_bf16_f32 v23, v31, v33
	v_cvt_pk_bf16_f32 v24, v35, v37
	v_cvt_pk_bf16_f32 v25, v39, v41
	v_mov_b32_e32 v27, v3
	ds_read2_b32 v[28:29], v8 offset0:49 offset1:57
	ds_read2_b32 v[30:31], v8 offset0:16 offset1:24
	ds_read2_b32 v[32:33], v8 offset0:82 offset1:90
	ds_read2_b32 v[34:35], v8 offset0:115 offset1:123
	ds_read2_b32 v[36:37], v8 offset0:148 offset1:156
	ds_read2_b32 v[38:39], v8 offset0:181 offset1:189
	ds_read2_b32 v[40:41], v8 offset0:214 offset1:222
	ds_read2_b32 v[42:43], v8 offset0:247 offset1:255
	v_lshl_add_u64 v[26:27], s[4:5], 0, v[26:27]
	v_lshl_add_u64 v[26:27], v[26:27], 0, v[44:45]
	v_or_b32_e32 v21, s12, v10
	global_store_dwordx4 v[26:27], v[22:25], off
	v_lshlrev_b32_e32 v26, 13, v21
	v_mov_b32_e32 v27, v3
	v_lshl_add_u64 v[26:27], s[4:5], 0, v[26:27]
	s_waitcnt lgkmcnt(6)
	v_cvt_pk_bf16_f32 v22, v30, v28
	s_waitcnt lgkmcnt(4)
	v_cvt_pk_bf16_f32 v23, v32, v34
	s_waitcnt lgkmcnt(2)
	v_cvt_pk_bf16_f32 v24, v36, v38
	s_waitcnt lgkmcnt(0)
	v_cvt_pk_bf16_f32 v25, v40, v42
	v_lshl_add_u64 v[26:27], v[26:27], 0, v[44:45]
	v_or_b32_e32 v21, s12, v11
	global_store_dwordx4 v[26:27], v[22:25], off
	v_lshlrev_b32_e32 v26, 13, v21
	v_mov_b32_e32 v27, v3
	v_lshl_add_u64 v[26:27], s[4:5], 0, v[26:27]
	v_cvt_pk_bf16_f32 v22, v31, v29
	v_cvt_pk_bf16_f32 v23, v33, v35
	v_cvt_pk_bf16_f32 v24, v37, v39
	v_cvt_pk_bf16_f32 v25, v41, v43
	v_lshl_add_u64 v[26:27], v[26:27], 0, v[44:45]
	global_store_dwordx4 v[26:27], v[22:25], off
	s_waitcnt lgkmcnt(0)
	s_cbranch_execnz .LBB0_8
	s_branch .LBB0_12

; #define LAS __attribute__((address_space(3)))
; __device__ __forceinline__ void p0_transpose_item(const float* W, int K, int N, bf16* WT, int mode, LAS float* scr, int item, int lane, const float* kscale = nullptr) {
;     const int nblk = N / 32, kb = item / nblk, nb = item % nblk, k0 = 64 * kb, n0 = 32 * nb;
;     const int rb = (mode == 0 || mode == 3 || mode == 4) ? n0 : ((n0 >> 7) * 256 + (n0 & 127) + (mode == 2 ? 128 : 0));
;     float wv[32];
; #pragma unroll
;     for (int i = 0; i < 32; ++i) wv[i] = W[(size_t)(k0 + 2 * i + (lane >> 5)) * N + n0 + (lane & 31)];
; #pragma unroll
;     for (int i = 0; i < 32; ++i) scr[(2 * i + (lane >> 5)) * 33 + (lane & 31)] = wv[i];
; template <int WHICH> __device__ __forceinline__ void convert_weights(const Frame& F, int gw, int ngw) {
;     ...
;     for (int it = gw; it < NIT; it += ngw) {
;         if (WHICH == 0) { if (it < I_1) p0_transpose_item(P_w_in, DM, 9248, P_W1, 0, scr, it, F.lane); else p0_transpose_item(P_w_out, DM, DM, P_W2, 4, scr, it - I_1, F.lane); }
.LBB0_12:
	s_mul_hi_i32 s12, s53, 0x71625345
	s_lshr_b32 s13, s12, 31
	s_ashr_i32 s12, s12, 7
	s_load_dwordx2 s[54:55], s[0:1], 0x48
	s_add_i32 s13, s12, s13
	s_lshl_b32 s12, s13, 6
	s_mulk_i32 s13, 0xdbe0
	s_add_i32 s14, s9, s13
	s_ashr_i32 s15, s14, 31
	s_lshl_b64 s[56:57], s[14:15], 2
	s_waitcnt lgkmcnt(0)
	s_add_u32 s54, s54, s56
	v_or_b32_e32 v21, s12, v1
	s_addc_u32 s55, s55, s57
	v_lshl_add_u64 v[22:23], s[54:55], 0, v[2:3]
	v_or_b32_e32 v26, 2, v21
	v_or_b32_e32 v28, 4, v21
	v_or_b32_e32 v30, 6, v21
	v_or_b32_e32 v32, 8, v21
	v_or_b32_e32 v34, 10, v21
	v_or_b32_e32 v36, 12, v21
	v_or_b32_e32 v38, 14, v21
	v_mad_i64_i32 v[24:25], s[54:55], v21, s52, v[22:23]
	v_mad_i64_i32 v[26:27], s[54:55], v26, s52, v[22:23]
	v_mad_i64_i32 v[28:29], s[54:55], v28, s52, v[22:23]
	v_mad_i64_i32 v[30:31], s[54:55], v30, s52, v[22:23]
	v_mad_i64_i32 v[32:33], s[54:55], v32, s52, v[22:23]
	v_mad_i64_i32 v[34:35], s[54:55], v34, s52, v[22:23]
	v_mad_i64_i32 v[36:37], s[54:55], v36, s52, v[22:23]
	v_mad_i64_i32 v[38:39], s[54:55], v38, s52, v[22:23]
	global_load_dword v40, v[24:25], off nt
	global_load_dword v41, v[26:27], off nt
	global_load_dword v42, v[28:29], off nt
	global_load_dword v43, v[30:31], off nt
	global_load_dword v44, v[32:33], off nt
	global_load_dword v45, v[34:35], off nt
	global_load_dword v46, v[36:37], off nt
	global_load_dword v47, v[38:39], off nt
	v_or_b32_e32 v24, 16, v21
	v_or_b32_e32 v26, 18, v21
	v_or_b32_e32 v28, 20, v21
	v_or_b32_e32 v30, 22, v21
	v_or_b32_e32 v32, 24, v21
	v_or_b32_e32 v34, 26, v21
	v_or_b32_e32 v36, 28, v21
	v_or_b32_e32 v38, 30, v21
	v_mad_i64_i32 v[24:25], s[54:55], v24, s52, v[22:23]
	v_mad_i64_i32 v[26:27], s[54:55], v26, s52, v[22:23]
	v_mad_i64_i32 v[28:29], s[54:55], v28, s52, v[22:23]
	v_mad_i64_i32 v[30:31], s[54:55], v30, s52, v[22:23]
	v_mad_i64_i32 v[32:33], s[54:55], v32, s52, v[22:23]
	v_mad_i64_i32 v[34:35], s[54:55], v34, s52, v[22:23]
	v_mad_i64_i32 v[36:37], s[54:55], v36, s52, v[22:23]
	v_mad_i64_i32 v[38:39], s[54:55], v38, s52, v[22:23]
	global_load_dword v48, v[24:25], off nt
	global_load_dword v49, v[26:27], off nt
	global_load_dword v50, v[28:29], off nt
	global_load_dword v51, v[30:31], off nt
	global_load_dword v52, v[32:33], off nt
	global_load_dword v53, v[34:35], off nt
	global_load_dword v54, v[36:37], off nt
	global_load_dword v55, v[38:39], off nt
	v_or_b32_e32 v24, 32, v21
	v_or_b32_e32 v26, 34, v21
	v_or_b32_e32 v28, 36, v21
	v_or_b32_e32 v30, 38, v21
	v_or_b32_e32 v32, 40, v21
	v_or_b32_e32 v34, 42, v21
	v_or_b32_e32 v36, 44, v21
	v_or_b32_e32 v38, 46, v21
	v_mad_i64_i32 v[24:25], s[54:55], v24, s52, v[22:23]
	v_mad_i64_i32 v[26:27], s[54:55], v26, s52, v[22:23]
	v_mad_i64_i32 v[28:29], s[54:55], v28, s52, v[22:23]
	v_mad_i64_i32 v[30:31], s[54:55], v30, s52, v[22:23]
	v_mad_i64_i32 v[32:33], s[54:55], v32, s52, v[22:23]
	v_mad_i64_i32 v[34:35], s[54:55], v34, s52, v[22:23]
	v_mad_i64_i32 v[36:37], s[54:55], v36, s52, v[22:23]
	v_mad_i64_i32 v[38:39], s[54:55], v38, s52, v[22:23]
	global_load_dword v56, v[24:25], off nt
	global_load_dword v57, v[26:27], off nt
	global_load_dword v58, v[28:29], off nt
	global_load_dword v59, v[30:31], off nt
	global_load_dword v60, v[32:33], off nt
	global_load_dword v61, v[34:35], off nt
	global_load_dword v62, v[36:37], off nt
	s_nop 0
	global_load_dword v38, v[38:39], off nt
	v_or_b32_e32 v24, 48, v21
	v_or_b32_e32 v26, 50, v21
	v_or_b32_e32 v28, 52, v21
	v_or_b32_e32 v30, 54, v21
	v_or_b32_e32 v32, 56, v21
	v_or_b32_e32 v34, 58, v21
	v_or_b32_e32 v36, 60, v21
	v_or_b32_e32 v21, 62, v21
	v_mad_i64_i32 v[24:25], s[54:55], v24, s52, v[22:23]
	v_mad_i64_i32 v[26:27], s[54:55], v26, s52, v[22:23]
	v_mad_i64_i32 v[28:29], s[54:55], v28, s52, v[22:23]
	v_mad_i64_i32 v[30:31], s[54:55], v30, s52, v[22:23]
	v_mad_i64_i32 v[32:33], s[54:55], v32, s52, v[22:23]
	v_mad_i64_i32 v[34:35], s[54:55], v34, s52, v[22:23]
	v_mad_i64_i32 v[36:37], s[54:55], v36, s52, v[22:23]
	v_mad_i64_i32 v[22:23], s[54:55], v21, s52, v[22:23]
	global_load_dword v21, v[24:25], off nt
	s_nop 0
	global_load_dword v24, v[26:27], off nt
	global_load_dword v25, v[28:29], off nt
	s_nop 0
	global_load_dword v26, v[30:31], off nt
	global_load_dword v27, v[32:33], off nt
	global_load_dword v28, v[34:35], off nt
	global_load_dword v29, v[36:37], off nt
	s_nop 0
	global_load_dword v22, v[22:23], off nt
	s_waitcnt vmcnt(30)
; #define LAS __attribute__((address_space(3)))
; #define LDS_WAIT() asm volatile("s_waitcnt lgkmcnt(0)" ::: "memory")
; __device__ __forceinline__ unsigned cvtpk(float lo, float hi) { f32x2_t v = {lo, hi}; bf16x2_t b = __builtin_convertvector(v, bf16x2_t); return __builtin_bit_cast(unsigned, b); }
; __device__ __forceinline__ void p0_transpose_item(const float* W, int K, int N, bf16* WT, int mode, LAS float* scr, int item, int lane, const float* kscale = nullptr) {
;     ...
;     for (int i = 0; i < 32; ++i) scr[(2 * i + (lane >> 5)) * 33 + (lane & 31)] = wv[i];
;     LDS_WAIT(); asm volatile("" ::: "memory");
;     const int c = lane & 7;
;     f32x4 ks0 = (f32x4){1.f, 1.f, 1.f, 1.f}, ks1 = ks0; if (kscale) { ks0 = *(const f32x4*)(kscale + k0 + 8 * c); ks1 = *(const f32x4*)(kscale + k0 + 8 * c + 4); }
; #pragma unroll
;     for (int j = 0; j < 4; ++j) { const int n = (lane >> 3) + 8 * j; const LAS float* s = scr + (8 * c) * 33 + n;
;         u32x4 o; o.x = cvtpk(s[0 * 33] * ks0.x, s[1 * 33] * ks0.y); o.y = cvtpk(s[2 * 33] * ks0.z, s[3 * 33] * ks0.w); o.z = cvtpk(s[4 * 33] * ks1.x, s[5 * 33] * ks1.y); o.w = cvtpk(s[6 * 33] * ks1.z, s[7 * 33] * ks1.w);
;         const int k0d = (mode == 4) ? ((k0 + 2048) & 4095) : k0;
;         const size_t dst = (mode == 3) ? ((size_t)(((rb + n) >> 8) * (K >> 6) + kb) * 256 + ((rb + n) & 255)) * 64 + 8 * c : (size_t)(rb + n) * K + k0d + 8 * c;
;         *(u32x4*)(WT + dst) = o; }
;     LDS_WAIT(); asm volatile("" ::: "memory");
	ds_write2_b32 v12, v40, v41 offset1:66
	s_waitcnt vmcnt(28)
	ds_write2_b32 v12, v42, v43 offset0:132 offset1:198
	s_waitcnt vmcnt(26)
	ds_write2_b32 v13, v44, v45 offset0:8 offset1:74
	s_waitcnt vmcnt(24)
	ds_write2_b32 v13, v46, v47 offset0:140 offset1:206
	s_waitcnt vmcnt(22)
	ds_write2_b32 v14, v48, v49 offset0:16 offset1:82
	s_waitcnt vmcnt(20)
	ds_write2_b32 v14, v50, v51 offset0:148 offset1:214
	s_waitcnt vmcnt(18)
	ds_write2_b32 v15, v52, v53 offset0:24 offset1:90
	s_waitcnt vmcnt(16)
	ds_write2_b32 v15, v54, v55 offset0:156 offset1:222
	s_waitcnt vmcnt(14)
	ds_write2_b32 v16, v56, v57 offset0:32 offset1:98
	s_waitcnt vmcnt(12)
	ds_write2_b32 v16, v58, v59 offset0:164 offset1:230
	s_waitcnt vmcnt(10)
	ds_write2_b32 v17, v60, v61 offset0:40 offset1:106
	s_waitcnt vmcnt(8)
	ds_write2_b32 v17, v62, v38 offset0:172 offset1:238
	s_waitcnt vmcnt(6)
	ds_write2_b32 v18, v21, v24 offset0:48 offset1:114
	s_waitcnt vmcnt(4)
	ds_write2_b32 v18, v25, v26 offset0:180 offset1:246
	s_waitcnt vmcnt(2)
	ds_write2_b32 v19, v27, v28 offset0:56 offset1:122
	s_waitcnt vmcnt(0)
	ds_write2_b32 v19, v29, v22 offset0:188 offset1:254
	s_waitcnt lgkmcnt(0)
	ds_read2_b32 v[26:27], v8 offset0:33 offset1:41
	ds_read2_b32 v[28:29], v8 offset1:8
	ds_read2_b32 v[30:31], v8 offset0:66 offset1:74
	ds_read2_b32 v[32:33], v8 offset0:99 offset1:107
	ds_read2_b32 v[34:35], v8 offset0:132 offset1:140
	ds_read2_b32 v[36:37], v8 offset0:165 offset1:173
	ds_read2_b32 v[38:39], v8 offset0:198 offset1:206
	ds_read2_b32 v[40:41], v8 offset0:231 offset1:239
	v_add_u32_e32 v42, s14, v7
	s_ashr_i32 s13, s12, 31
	v_ashrrev_i32_e32 v43, 31, v42
	v_lshl_add_u64 v[44:45], s[12:13], 1, v[4:5]
	v_lshlrev_b64 v[46:47], 13, v[42:43]
	s_waitcnt lgkmcnt(6)
	v_cvt_pk_bf16_f32 v22, v28, v26
	s_waitcnt lgkmcnt(4)
	v_cvt_pk_bf16_f32 v23, v30, v32
	s_waitcnt lgkmcnt(2)
	v_cvt_pk_bf16_f32 v24, v34, v36
	s_waitcnt lgkmcnt(0)
	v_cvt_pk_bf16_f32 v25, v38, v40
	v_lshl_add_u64 v[46:47], v[44:45], 0, v[46:47]
	v_add_u32_e32 v26, 8, v42
	global_store_dwordx4 v[46:47], v[22:25], off
	s_nop 1
	v_cvt_pk_bf16_f32 v22, v29, v27
	v_ashrrev_i32_e32 v27, 31, v26
	v_cvt_pk_bf16_f32 v23, v31, v33
	v_cvt_pk_bf16_f32 v24, v35, v37
	v_cvt_pk_bf16_f32 v25, v39, v41
	v_lshlrev_b64 v[26:27], 13, v[26:27]
	ds_read2_b32 v[28:29], v8 offset0:49 offset1:57
	ds_read2_b32 v[30:31], v8 offset0:16 offset1:24
	ds_read2_b32 v[32:33], v8 offset0:82 offset1:90
	ds_read2_b32 v[34:35], v8 offset0:115 offset1:123
	ds_read2_b32 v[36:37], v8 offset0:148 offset1:156
	ds_read2_b32 v[38:39], v8 offset0:181 offset1:189
	ds_read2_b32 v[40:41], v8 offset0:214 offset1:222
	ds_read2_b32 v[46:47], v8 offset0:247 offset1:255
	v_lshl_add_u64 v[26:27], v[44:45], 0, v[26:27]
	global_store_dwordx4 v[26:27], v[22:25], off
	v_add_u32_e32 v26, 16, v42
	v_ashrrev_i32_e32 v27, 31, v26
	v_lshlrev_b64 v[26:27], 13, v[26:27]
	s_waitcnt lgkmcnt(6)
	v_cvt_pk_bf16_f32 v22, v30, v28
	s_waitcnt lgkmcnt(4)
	v_cvt_pk_bf16_f32 v23, v32, v34
	s_waitcnt lgkmcnt(2)
	v_cvt_pk_bf16_f32 v24, v36, v38
	s_waitcnt lgkmcnt(0)
	v_cvt_pk_bf16_f32 v25, v40, v46
	v_lshl_add_u64 v[26:27], v[44:45], 0, v[26:27]
	global_store_dwordx4 v[26:27], v[22:25], off
	v_add_u32_e32 v26, 24, v42
	v_ashrrev_i32_e32 v27, 31, v26
	v_lshlrev_b64 v[26:27], 13, v[26:27]
	v_cvt_pk_bf16_f32 v22, v31, v29
	v_cvt_pk_bf16_f32 v23, v33, v35
	v_cvt_pk_bf16_f32 v24, v37, v39
	v_cvt_pk_bf16_f32 v25, v41, v47
	v_lshl_add_u64 v[26:27], v[44:45], 0, v[26:27]
	global_store_dwordx4 v[26:27], v[22:25], off
	s_waitcnt lgkmcnt(0)
	s_branch .LBB0_8

; __device__ __forceinline__ void rms_regs_to_bf16(const f32x4 (&v)[16], const float* w, bf16* orow, int lane) {
;     float s = 0.f;
; #pragma unroll
;     for (int j = 0; j < 16; ++j) s += (v[j].x * v[j].x + v[j].y * v[j].y) + (v[j].z * v[j].z + v[j].w * v[j].w);
; __device__ __forceinline__ void rms_row_to_bf16(const float* xrow, const float* w, bf16* orow, int lane) {
;     const f32x4* xr = (const f32x4*)xrow + 2 * lane; f32x4 v[16];
; #pragma unroll
;     for (int j = 0; j < 8; ++j) { v[2 * j] = xr[128 * j]; v[2 * j + 1] = xr[128 * j + 1]; }
;     rms_regs_to_bf16(v, w, orow, lane);
.LBB0_15:
	global_load_dwordx4 v[26:29], v66, s[4:5]
	global_load_dwordx4 v[22:25], v66, s[4:5] offset:16
	global_load_dwordx4 v[2:5], v66, s[4:5] offset:2064
	global_load_dwordx4 v[6:9], v66, s[4:5] offset:2048
	v_lshl_add_u64 v[10:11], s[4:5], 0, v[66:67]
	v_add_co_u32_e32 v12, vcc, 0x1000, v10
	v_lshl_add_u64 v[16:17], v[10:11], 0, s[16:17]
	s_nop 0
	v_addc_co_u32_e32 v13, vcc, 0, v11, vcc
	v_lshl_add_u64 v[14:15], v[10:11], 0, s[14:15]
	global_load_dwordx4 v[18:21], v[16:17], off offset:16 nt
	global_load_dwordx4 v[42:45], v[14:15], off offset:16 nt
	global_load_dwordx4 v[54:57], v[12:13], off nt
	global_load_dwordx4 v[58:61], v[12:13], off offset:2048 nt
	v_add_co_u32_e32 v14, vcc, s36, v10
	s_mov_b64 s[4:5], vcc
	v_add_co_u32_e32 v92, vcc, s37, v10
	v_lshl_add_u64 v[12:13], v[10:11], 0, s[18:19]
	s_nop 0
	v_addc_co_u32_e32 v93, vcc, 0, v11, vcc
	global_load_dwordx4 v[34:37], v[12:13], off offset:16 nt
	global_load_dwordx4 v[46:49], v[92:93], off offset:-4096 nt
	v_addc_co_u32_e64 v15, vcc, 0, v11, s[4:5]
	global_load_dwordx4 v[30:33], v[14:15], off offset:2048 nt
	v_lshl_add_u64 v[94:95], v[10:11], 0, s[24:25]
	v_lshl_add_u64 v[96:97], v[10:11], 0, s[20:21]
	v_lshl_add_u64 v[98:99], v[10:11], 0, s[22:23]
	global_load_dwordx4 v[10:13], v[94:95], off offset:16 nt
	global_load_dwordx4 v[50:53], v[92:93], off nt
	global_load_dwordx4 v[62:65], v[96:97], off offset:16 nt
	global_load_dwordx4 v[38:41], v[98:99], off offset:16 nt
	global_load_dwordx4 v[14:17], v[92:93], off offset:2048 nt
	s_waitcnt vmcnt(15)
	v_pk_mul_f32 v[92:93], v[28:29], v[28:29]
	v_pk_mul_f32 v[94:95], v[26:27], v[26:27]
	s_waitcnt vmcnt(14)
	v_pk_mul_f32 v[96:97], v[24:25], v[24:25]
	v_pk_mul_f32 v[98:99], v[22:23], v[22:23]
	s_waitcnt vmcnt(12)
	v_mul_f32_e32 v84, v7, v7
	v_mul_f32_e32 v100, v9, v9
	v_pk_mov_b32 v[102:103], v[94:95], v[92:93] op_sel:[1,0]
	v_mov_b32_e32 v95, v93
	v_pk_mov_b32 v[92:93], v[98:99], v[96:97] op_sel:[1,0]
	v_mov_b32_e32 v99, v97
	v_mul_f32_e32 v104, v4, v4
	v_mul_f32_e32 v105, v5, v5
	v_pk_fma_f32 v[96:97], v[6:7], v[6:7], v[84:85] op_sel_hi:[1,1,0]
	v_pk_fma_f32 v[100:101], v[8:9], v[8:9], v[100:101] op_sel_hi:[1,1,0]
	v_pk_add_f32 v[94:95], v[102:103], v[94:95]
	v_pk_add_f32 v[92:93], v[92:93], v[98:99]
	v_mul_f32_e32 v112, v2, v2
	v_mul_f32_e32 v113, v3, v3
	v_mov_b32_e32 v97, v104
	v_mov_b32_e32 v101, v105
	v_pk_add_f32 v[94:95], v[94:95], v[94:95] op_sel:[0,1] op_sel_hi:[1,0]
	v_pk_add_f32 v[92:93], v[92:93], v[92:93] op_sel:[0,1] op_sel_hi:[1,0]
	v_pk_add_f32 v[96:97], v[96:97], v[100:101]
	s_waitcnt vmcnt(9)
	v_pk_mul_f32 v[100:101], v[56:57], v[56:57]
	v_pk_mul_f32 v[106:107], v[54:55], v[54:55]
	v_mov_b32_e32 v95, v112
	v_mov_b32_e32 v93, v113
	v_pk_mov_b32 v[110:111], v[106:107], v[100:101] op_sel:[1,0]
	v_mov_b32_e32 v107, v101
	v_pk_add_f32 v[92:93], v[94:95], v[92:93]
	v_pk_mul_f32 v[98:99], v[20:21], v[20:21]
	v_pk_mul_f32 v[102:103], v[18:19], v[18:19]
	v_mul_f32_e32 v84, v43, v43
	v_mul_f32_e32 v104, v45, v45
	v_pk_add_f32 v[94:95], v[110:111], v[106:107]
	v_pk_add_f32 v[92:93], v[92:93], v[96:97]
	v_pk_mov_b32 v[108:109], v[102:103], v[98:99] op_sel:[1,0]
	v_mov_b32_e32 v103, v99
	v_pk_fma_f32 v[98:99], v[42:43], v[42:43], v[84:85] op_sel_hi:[1,1,0]
	v_pk_fma_f32 v[104:105], v[44:45], v[44:45], v[104:105] op_sel_hi:[1,1,0]
	s_waitcnt vmcnt(8)
	v_mul_f32_e32 v114, v59, v59
	v_pk_add_f32 v[94:95], v[94:95], v[94:95] op_sel:[0,1] op_sel_hi:[1,0]
	v_pk_add_f32 v[92:93], v[92:93], v[92:93] op_sel:[0,1] op_sel_hi:[1,0]
	v_mul_f32_e32 v99, v60, v60
	v_mul_f32_e32 v105, v61, v61
	v_mov_b32_e32 v95, v114
	v_mul_f32_e32 v93, v58, v58
	v_pk_add_f32 v[98:99], v[98:99], v[104:105]
	v_pk_add_f32 v[92:93], v[92:93], v[94:95]
	v_pk_add_f32 v[100:101], v[108:109], v[102:103]
	v_pk_add_f32 v[92:93], v[92:93], v[98:99]
	v_pk_add_f32 v[94:95], v[100:101], v[100:101] op_sel:[0,1] op_sel_hi:[1,0]
	v_pk_add_f32 v[92:93], v[92:93], v[92:93] op_sel:[0,1] op_sel_hi:[1,0]
	s_waitcnt vmcnt(7)
	v_mul_f32_e32 v95, v35, v35
	v_mul_f32_e32 v93, v34, v34
	s_waitcnt vmcnt(6)
	v_mul_f32_e32 v84, v47, v47
	v_pk_add_f32 v[92:93], v[92:93], v[94:95]
	v_pk_fma_f32 v[94:95], v[46:47], v[46:47], v[84:85] op_sel_hi:[1,1,0]
	v_mul_f32_e32 v84, v49, v49
	v_pk_fma_f32 v[96:97], v[48:49], v[48:49], v[84:85] op_sel_hi:[1,1,0]
	v_mul_f32_e32 v95, v36, v36
	v_mul_f32_e32 v97, v37, v37
	v_pk_add_f32 v[94:95], v[94:95], v[96:97]
	s_waitcnt vmcnt(5)
	v_pk_mul_f32 v[96:97], v[30:31], v[30:31]
	v_pk_add_f32 v[92:93], v[92:93], v[94:95]
	v_pk_mul_f32 v[94:95], v[32:33], v[32:33]
	v_pk_add_f32 v[92:93], v[92:93], v[92:93] op_sel:[0,1] op_sel_hi:[1,0]
	v_pk_mov_b32 v[98:99], v[96:97], v[94:95] op_sel:[1,0]
	v_mov_b32_e32 v97, v95
	v_pk_add_f32 v[94:95], v[98:99], v[96:97]
	s_waitcnt vmcnt(3)
	v_mul_f32_e32 v93, v50, v50
	v_pk_add_f32 v[94:95], v[94:95], v[94:95] op_sel:[0,1] op_sel_hi:[1,0]
	s_waitcnt vmcnt(2)
	v_mul_f32_e32 v84, v63, v63
	v_mul_f32_e32 v95, v51, v51
	v_pk_add_f32 v[92:93], v[92:93], v[94:95]
	v_pk_fma_f32 v[94:95], v[62:63], v[62:63], v[84:85] op_sel_hi:[1,1,0]
	v_mul_f32_e32 v84, v65, v65
	v_pk_fma_f32 v[96:97], v[64:65], v[64:65], v[84:85] op_sel_hi:[1,1,0]
	v_mul_f32_e32 v95, v52, v52
	v_mul_f32_e32 v97, v53, v53
	v_pk_add_f32 v[94:95], v[94:95], v[96:97]
	s_waitcnt vmcnt(1)
	v_pk_mul_f32 v[96:97], v[38:39], v[38:39]
	v_pk_add_f32 v[92:93], v[92:93], v[94:95]
	v_pk_mul_f32 v[94:95], v[40:41], v[40:41]
	s_waitcnt vmcnt(0)
; __device__ __forceinline__ unsigned cvtpk(float lo, float hi) { f32x2_t v = {lo, hi}; bf16x2_t b = __builtin_convertvector(v, bf16x2_t); return __builtin_bit_cast(unsigned, b); }
; __device__ __forceinline__ float wave_sum(float v) {
; #pragma unroll
;     for (int o = 1; o < 64; o <<= 1) v += __shfl_xor(v, o);
;     return v;
; __device__ __forceinline__ void rms_regs_to_bf16(const f32x4 (&v)[16], const float* w, bf16* orow, int lane) {
;     ...
;     const float rstd = 1.0f / sqrtf(wave_sum(s) * (1.0f / DM) + EPS);
;     const f32x4* wr = (const f32x4*)w + 2 * lane; u32x4* o16 = (u32x4*)orow + lane;
; #pragma unroll
;     for (int j = 0; j < 8; ++j) { const f32x4 w0 = wr[128 * j], w1 = wr[128 * j + 1]; const f32x4 a = v[2 * j], b = v[2 * j + 1]; u32x4 o;
;         o.x = cvtpk(a.x * rstd * w0.x, a.y * rstd * w0.y); o.y = cvtpk(a.z * rstd * w0.z, a.w * rstd * w0.w); o.z = cvtpk(b.x * rstd * w1.x, b.y * rstd * w1.y); o.w = cvtpk(b.z * rstd * w1.z, b.w * rstd * w1.w); o16[64 * j] = o; }
	v_mul_f32_e32 v84, v15, v15
	v_pk_mov_b32 v[98:99], v[96:97], v[94:95] op_sel:[1,0]
	v_mov_b32_e32 v97, v95
	v_pk_add_f32 v[94:95], v[98:99], v[96:97]
	v_pk_fma_f32 v[98:99], v[14:15], v[14:15], v[84:85] op_sel_hi:[1,1,0]
	v_mul_f32_e32 v84, v17, v17
	v_pk_add_f32 v[92:93], v[92:93], v[92:93] op_sel:[0,1] op_sel_hi:[1,0]
	v_pk_add_f32 v[94:95], v[94:95], v[94:95] op_sel:[0,1] op_sel_hi:[1,0]
	v_pk_fma_f32 v[100:101], v[16:17], v[16:17], v[84:85] op_sel_hi:[1,1,0]
	v_mul_f32_e32 v93, v10, v10
	v_mul_f32_e32 v95, v11, v11
	v_mul_f32_e32 v99, v12, v12
	v_mul_f32_e32 v101, v13, v13
	v_pk_add_f32 v[96:97], v[92:93], v[94:95]
	v_pk_add_f32 v[98:99], v[98:99], v[100:101]
	global_load_dwordx4 v[92:95], v[70:71], off
	v_pk_add_f32 v[96:97], v[96:97], v[98:99]
	s_nop 0
	v_add_f32_e32 v84, v96, v97
	global_load_dwordx4 v[96:99], v[70:71], off offset:16
	ds_bpermute_b32 v100, v1, v84
	s_waitcnt lgkmcnt(0)
	v_add_f32_e32 v84, v84, v100
	ds_bpermute_b32 v100, v85, v84
	s_waitcnt lgkmcnt(0)
	v_add_f32_e32 v84, v84, v100
	ds_bpermute_b32 v100, v86, v84
	s_waitcnt lgkmcnt(0)
	v_add_f32_e32 v84, v84, v100
	ds_bpermute_b32 v100, v87, v84
	s_waitcnt lgkmcnt(0)
	v_add_f32_e32 v84, v84, v100
	ds_bpermute_b32 v100, v88, v84
	s_waitcnt lgkmcnt(0)
	v_add_f32_e32 v84, v84, v100
	ds_bpermute_b32 v100, v89, v84
	s_waitcnt lgkmcnt(0)
	v_add_f32_e32 v84, v84, v100
	v_fmamk_f32 v84, v84, 0x39800000, v90
	v_mul_f32_e32 v100, 0x4f800000, v84
	v_cmp_gt_f32_e32 vcc, s38, v84
	s_nop 1
	v_cndmask_b32_e32 v84, v84, v100, vcc
	v_sqrt_f32_e32 v100, v84
	s_nop 0
	v_add_u32_e32 v101, -1, v100
	v_fma_f32 v102, -v101, v100, v84
	v_cmp_ge_f32_e64 s[4:5], 0, v102
	v_add_u32_e32 v102, 1, v100
	s_nop 0
	v_cndmask_b32_e64 v101, v100, v101, s[4:5]
	v_fma_f32 v100, -v102, v100, v84
	v_cmp_lt_f32_e64 s[4:5], 0, v100
	s_nop 1
	v_cndmask_b32_e64 v100, v101, v102, s[4:5]
	v_mul_f32_e32 v101, 0x37800000, v100
	v_cndmask_b32_e32 v100, v100, v101, vcc
	v_cmp_class_f32_e32 vcc, v84, v91
	s_nop 1
	v_cndmask_b32_e32 v84, v100, v84, vcc
	v_div_scale_f32 v100, s[4:5], v84, v84, 1.0
	v_rcp_f32_e32 v101, v100
	s_lshl_b64 s[4:5], s[30:31], 13
	s_add_u32 s8, s8, s10
	s_addc_u32 s9, s9, s11
	v_fma_f32 v102, -v100, v101, 1.0
	v_fmac_f32_e32 v101, v102, v101
	v_div_scale_f32 v102, vcc, 1.0, v84, 1.0
	v_mul_f32_e32 v103, v102, v101
	v_fma_f32 v104, -v100, v103, v102
	v_fmac_f32_e32 v103, v104, v101
	v_fma_f32 v100, -v100, v103, v102
	v_div_fmas_f32 v100, v100, v101, v103
	v_div_fixup_f32 v84, v100, v84, 1.0
	v_pk_mul_f32 v[26:27], v[26:27], v[84:85] op_sel_hi:[1,0]
	v_pk_mul_f32 v[28:29], v[28:29], v[84:85] op_sel_hi:[1,0]
	v_pk_mul_f32 v[22:23], v[22:23], v[84:85] op_sel_hi:[1,0]
	v_pk_mul_f32 v[24:25], v[24:25], v[84:85] op_sel_hi:[1,0]
	s_waitcnt vmcnt(1)
	v_pk_mul_f32 v[26:27], v[92:93], v[26:27]
	v_pk_mul_f32 v[28:29], v[94:95], v[28:29]
	s_waitcnt vmcnt(0)
	v_pk_mul_f32 v[92:93], v[96:97], v[22:23]
	v_pk_mul_f32 v[94:95], v[98:99], v[24:25]
	v_cvt_pk_bf16_f32 v22, v26, v27
	v_cvt_pk_bf16_f32 v23, v28, v29
	v_cvt_pk_bf16_f32 v24, v92, v93
	v_cvt_pk_bf16_f32 v25, v94, v95
	v_lshl_add_u64 v[92:93], v[68:69], 0, s[4:5]
	global_store_dwordx4 v[92:93], v[22:25], off
	global_load_dwordx4 v[22:25], v[70:71], off offset:2048
	s_nop 0
	global_load_dwordx4 v[26:29], v[70:71], off offset:2064
	v_pk_mul_f32 v[6:7], v[6:7], v[84:85] op_sel_hi:[1,0]
	v_pk_mul_f32 v[8:9], v[8:9], v[84:85] op_sel_hi:[1,0]
	v_pk_mul_f32 v[2:3], v[2:3], v[84:85] op_sel_hi:[1,0]
	v_pk_mul_f32 v[4:5], v[4:5], v[84:85] op_sel_hi:[1,0]
	v_pk_mul_f32 v[18:19], v[18:19], v[84:85] op_sel_hi:[1,0]
	v_pk_mul_f32 v[20:21], v[20:21], v[84:85] op_sel_hi:[1,0]
	s_add_u32 s26, s26, s28
	v_pk_mul_f32 v[14:15], v[14:15], v[84:85] op_sel_hi:[1,0]
	v_pk_mul_f32 v[16:17], v[16:17], v[84:85] op_sel_hi:[1,0]
	v_pk_mul_f32 v[10:11], v[10:11], v[84:85] op_sel_hi:[1,0]
	v_pk_mul_f32 v[12:13], v[12:13], v[84:85] op_sel_hi:[1,0]
	s_addc_u32 s27, s27, s29
	s_cmpk_lt_i32 s8, 0x2400
	s_waitcnt vmcnt(1)
	v_pk_mul_f32 v[6:7], v[22:23], v[6:7]
	v_pk_mul_f32 v[8:9], v[24:25], v[8:9]
	s_waitcnt vmcnt(0)
; __device__ __forceinline__ unsigned cvtpk(float lo, float hi) { f32x2_t v = {lo, hi}; bf16x2_t b = __builtin_convertvector(v, bf16x2_t); return __builtin_bit_cast(unsigned, b); }
; __device__ __forceinline__ void rms_regs_to_bf16(const f32x4 (&v)[16], const float* w, bf16* orow, int lane) {
;     ...
;     const f32x4* wr = (const f32x4*)w + 2 * lane; u32x4* o16 = (u32x4*)orow + lane;
; #pragma unroll
;     for (int j = 0; j < 8; ++j) { const f32x4 w0 = wr[128 * j], w1 = wr[128 * j + 1]; const f32x4 a = v[2 * j], b = v[2 * j + 1]; u32x4 o;
;         o.x = cvtpk(a.x * rstd * w0.x, a.y * rstd * w0.y); o.y = cvtpk(a.z * rstd * w0.z, a.w * rstd * w0.w); o.z = cvtpk(b.x * rstd * w1.x, b.y * rstd * w1.y); o.w = cvtpk(b.z * rstd * w1.z, b.w * rstd * w1.w); o16[64 * j] = o; }
; __device__ __forceinline__ void p0_prologue(const Frame& F, const Ptrs& P) {
;     ...
;     for (int m = gw; m < M; m += NGW) { const float* xr = (m < MP) ? P_x_prompt + (size_t)m * DM : P_x_sample + (size_t)(m - MP) * DM; rms_row_to_bf16(xr, P_mix_nw, P_XN + (size_t)m * DM, F.lane); }
	v_pk_mul_f32 v[22:23], v[26:27], v[2:3]
	v_pk_mul_f32 v[24:25], v[28:29], v[4:5]
	v_cvt_pk_bf16_f32 v2, v6, v7
	v_cvt_pk_bf16_f32 v3, v8, v9
	v_cvt_pk_bf16_f32 v4, v22, v23
	v_cvt_pk_bf16_f32 v5, v24, v25
	global_store_dwordx4 v[92:93], v[2:5], off offset:1024
	global_load_dwordx4 v[2:5], v[72:73], off
	s_nop 0
	global_load_dwordx4 v[6:9], v[72:73], off offset:16
	v_pk_mul_f32 v[22:23], v[54:55], v[84:85] op_sel_hi:[1,0]
	v_pk_mul_f32 v[24:25], v[56:57], v[84:85] op_sel_hi:[1,0]
	v_pk_mul_f32 v[26:27], v[42:43], v[84:85] op_sel_hi:[1,0]
	v_pk_mul_f32 v[28:29], v[44:45], v[84:85] op_sel_hi:[1,0]
	s_waitcnt vmcnt(1)
	v_pk_mul_f32 v[2:3], v[2:3], v[22:23]
	v_pk_mul_f32 v[4:5], v[4:5], v[24:25]
	s_waitcnt vmcnt(0)
	v_pk_mul_f32 v[6:7], v[6:7], v[26:27]
	v_pk_mul_f32 v[8:9], v[8:9], v[28:29]
	v_cvt_pk_bf16_f32 v2, v2, v3
	v_cvt_pk_bf16_f32 v3, v4, v5
	v_cvt_pk_bf16_f32 v4, v6, v7
	v_cvt_pk_bf16_f32 v5, v8, v9
	global_store_dwordx4 v[92:93], v[2:5], off offset:2048
	global_load_dwordx4 v[2:5], v[74:75], off
	s_nop 0
	global_load_dwordx4 v[6:9], v[74:75], off offset:16
	v_pk_mul_f32 v[22:23], v[58:59], v[84:85] op_sel_hi:[1,0]
	v_pk_mul_f32 v[24:25], v[60:61], v[84:85] op_sel_hi:[1,0]
	v_pk_mul_f32 v[26:27], v[36:37], v[84:85] op_sel_hi:[1,0]
	s_waitcnt vmcnt(1)
	v_pk_mul_f32 v[2:3], v[22:23], v[2:3]
	v_pk_mul_f32 v[4:5], v[24:25], v[4:5]
	s_waitcnt vmcnt(0)
	v_pk_mul_f32 v[6:7], v[18:19], v[6:7]
	v_pk_mul_f32 v[8:9], v[20:21], v[8:9]
	v_cvt_pk_bf16_f32 v2, v2, v3
	v_cvt_pk_bf16_f32 v3, v4, v5
	v_cvt_pk_bf16_f32 v4, v6, v7
	v_cvt_pk_bf16_f32 v5, v8, v9
	global_store_dwordx4 v[92:93], v[2:5], off offset:3072
	global_load_dwordx4 v[2:5], v[76:77], off
	s_nop 0
	global_load_dwordx4 v[6:9], v[76:77], off offset:16
	v_pk_mul_f32 v[20:21], v[46:47], v[84:85] op_sel_hi:[1,0]
	v_pk_mul_f32 v[22:23], v[48:49], v[84:85] op_sel_hi:[1,0]
	v_pk_mul_f32 v[24:25], v[34:35], v[84:85] op_sel_hi:[1,0]
	v_add_co_u32_e32 v18, vcc, s33, v92
	s_waitcnt vmcnt(1)
	v_pk_mul_f32 v[2:3], v[20:21], v[2:3]
	v_pk_mul_f32 v[4:5], v[22:23], v[4:5]
	s_waitcnt vmcnt(0)
	v_pk_mul_f32 v[6:7], v[24:25], v[6:7]
	v_pk_mul_f32 v[8:9], v[26:27], v[8:9]
	v_addc_co_u32_e32 v19, vcc, 0, v93, vcc
	v_cvt_pk_bf16_f32 v2, v2, v3
	v_cvt_pk_bf16_f32 v3, v4, v5
	v_cvt_pk_bf16_f32 v4, v6, v7
	v_cvt_pk_bf16_f32 v5, v8, v9
	global_store_dwordx4 v[18:19], v[2:5], off
	global_load_dwordx4 v[2:5], v[78:79], off
	s_nop 0
	global_load_dwordx4 v[6:9], v[78:79], off offset:16
	v_pk_mul_f32 v[20:21], v[30:31], v[84:85] op_sel_hi:[1,0]
	v_pk_mul_f32 v[22:23], v[32:33], v[84:85] op_sel_hi:[1,0]
	v_pk_mul_f32 v[24:25], v[62:63], v[84:85] op_sel_hi:[1,0]
	v_pk_mul_f32 v[26:27], v[64:65], v[84:85] op_sel_hi:[1,0]
	s_waitcnt vmcnt(1)
	v_pk_mul_f32 v[2:3], v[20:21], v[2:3]
	v_pk_mul_f32 v[4:5], v[22:23], v[4:5]
	s_waitcnt vmcnt(0)
	v_pk_mul_f32 v[6:7], v[24:25], v[6:7]
	v_pk_mul_f32 v[8:9], v[26:27], v[8:9]
	v_cvt_pk_bf16_f32 v2, v2, v3
	v_cvt_pk_bf16_f32 v3, v4, v5
	v_cvt_pk_bf16_f32 v4, v6, v7
	v_cvt_pk_bf16_f32 v5, v8, v9
	global_store_dwordx4 v[18:19], v[2:5], off offset:1024
	global_load_dwordx4 v[2:5], v[80:81], off
	s_nop 0
	global_load_dwordx4 v[6:9], v[80:81], off offset:16
	v_pk_mul_f32 v[20:21], v[50:51], v[84:85] op_sel_hi:[1,0]
	v_pk_mul_f32 v[22:23], v[52:53], v[84:85] op_sel_hi:[1,0]
	v_pk_mul_f32 v[24:25], v[38:39], v[84:85] op_sel_hi:[1,0]
	v_pk_mul_f32 v[26:27], v[40:41], v[84:85] op_sel_hi:[1,0]
	s_waitcnt vmcnt(1)
	v_pk_mul_f32 v[2:3], v[20:21], v[2:3]
	v_pk_mul_f32 v[4:5], v[22:23], v[4:5]
	s_waitcnt vmcnt(0)
	v_pk_mul_f32 v[6:7], v[24:25], v[6:7]
	v_pk_mul_f32 v[8:9], v[26:27], v[8:9]
	v_cvt_pk_bf16_f32 v2, v2, v3
	v_cvt_pk_bf16_f32 v3, v4, v5
	v_cvt_pk_bf16_f32 v4, v6, v7
	v_cvt_pk_bf16_f32 v5, v8, v9
	global_store_dwordx4 v[18:19], v[2:5], off offset:2048
	global_load_dwordx4 v[2:5], v[82:83], off
	s_nop 0
	global_load_dwordx4 v[6:9], v[82:83], off offset:16
	s_waitcnt vmcnt(1)
	v_pk_mul_f32 v[2:3], v[14:15], v[2:3]
	v_pk_mul_f32 v[4:5], v[16:17], v[4:5]
	s_waitcnt vmcnt(0)
	v_pk_mul_f32 v[6:7], v[10:11], v[6:7]
	v_pk_mul_f32 v[8:9], v[12:13], v[8:9]
	v_cvt_pk_bf16_f32 v2, v2, v3
	v_cvt_pk_bf16_f32 v3, v4, v5
	v_cvt_pk_bf16_f32 v4, v6, v7
	v_cvt_pk_bf16_f32 v5, v8, v9
	global_store_dwordx4 v[18:19], v[2:5], off offset:3072
	s_cbranch_scc0 .LBB0_20

; #define LAS __attribute__((address_space(3)))
; #define LDS_WAIT() asm volatile("s_waitcnt lgkmcnt(0)" ::: "memory")
; __device__ __forceinline__ void p0_transpose_item(const float* W, int K, int N, bf16* WT, int mode, LAS float* scr, int item, int lane, const float* kscale = nullptr) {
;     const int nblk = N / 32, kb = item / nblk, nb = item % nblk, k0 = 64 * kb, n0 = 32 * nb;
;     const int rb = (mode == 0 || mode == 3 || mode == 4) ? n0 : ((n0 >> 7) * 256 + (n0 & 127) + (mode == 2 ? 128 : 0));
;     float wv[32];
; #pragma unroll
;     for (int i = 0; i < 32; ++i) wv[i] = W[(size_t)(k0 + 2 * i + (lane >> 5)) * N + n0 + (lane & 31)];
; #pragma unroll
;     for (int i = 0; i < 32; ++i) scr[(2 * i + (lane >> 5)) * 33 + (lane & 31)] = wv[i];
;     LDS_WAIT(); asm volatile("" ::: "memory");
;     const int c = lane & 7;
;     f32x4 ks0 = (f32x4){1.f, 1.f, 1.f, 1.f}, ks1 = ks0; if (kscale) { ks0 = *(const f32x4*)(kscale + k0 + 8 * c); ks1 = *(const f32x4*)(kscale + k0 + 8 * c + 4); }
; template <int WHICH> __device__ __forceinline__ void convert_weights_dyn(const Frame& F, gu32* ctr) {
;     LAS float* scr = (LAS float*)(F.lds + RING_OFF + F.wave * 16384);
;     constexpr int NIT = WHICH == 3 ? 2 * I_3 : I_4;
;     for (;;) {
;         unsigned v = 0u; if (F.lane == 0) v = __hip_atomic_fetch_add(ctr, 8u, RLX_AGENT);
;         const int it0 = (int)__builtin_amdgcn_readfirstlane(v); if (it0 >= NIT) break;
; #pragma unroll 1
;         for (int k = 0; k < 8; ++k) { const int it = it0 + k; if (it >= NIT) break;
;             if (WHICH == 3) { if (it < I_3) p0_transpose_item(P_w_gate, DM, DFF, P_W3, 1, scr, it, F.lane, P_ffn_nw); else p0_transpose_item(P_w_up, DM, DFF, P_W3, 2, scr, it - I_3, F.lane, P_ffn_nw); }
;             else p0_transpose_item(P_w_down, DFF, DM, P_W4, 0, scr, it, F.lane); }
.LBB0_122:
	s_add_i32 s16, s55, s56
	s_cmp_gt_i32 s16, 0xabff
	s_mov_b64 s[12:13], -1
	s_cbranch_scc1 .LBB0_121
	s_load_dwordx2 s[12:13], s[0:1], 0xa0
	s_cmpk_gt_i32 s16, 0x55ff
	s_mov_b64 s[14:15], -1
	s_cbranch_scc0 .LBB0_128
	s_add_i32 s10, s16, 0xaa00
	s_and_b32 s14, s10, 0xffff
	s_mul_i32 s14, s14, 0xbe83
	s_load_dwordx2 s[58:59], s[0:1], 0xb0
	s_lshr_b32 s15, s14, 24
	s_mul_i32 s14, s15, 0x158
	s_sub_i32 s10, s10, s14
	s_and_b32 s14, s10, 0xffff
	s_lshl_b32 s10, s15, 6
	s_lshl_b32 s15, s14, 7
	s_waitcnt lgkmcnt(0)
	s_add_u32 s58, s58, s15
	v_or_b32_e32 v4, s10, v1
	s_addc_u32 s59, s59, 0
	v_lshl_add_u64 v[2:3], s[58:59], 0, v[10:11]
	v_mul_u32_u24_e32 v4, 0xac00, v4
	v_mov_b32_e32 v5, v11
	v_lshl_add_u64 v[2:3], v[2:3], 0, v[4:5]
	v_add_co_u32_e32 v4, vcc, s19, v2
	s_cmp_eq_u64 s[12:13], 0
	s_nop 0
	v_addc_co_u32_e32 v5, vcc, 0, v3, vcc
	v_add_co_u32_e32 v6, vcc, s20, v2
	s_nop 1
	v_addc_co_u32_e32 v7, vcc, 0, v3, vcc
	v_add_co_u32_e32 v8, vcc, s21, v2
	s_nop 1
	v_addc_co_u32_e32 v9, vcc, 0, v3, vcc
	v_add_co_u32_e32 v28, vcc, s22, v2
	s_nop 1
	v_addc_co_u32_e32 v29, vcc, 0, v3, vcc
	v_add_co_u32_e32 v30, vcc, s23, v2
	s_nop 1
	v_addc_co_u32_e32 v31, vcc, 0, v3, vcc
	v_add_co_u32_e32 v32, vcc, s24, v2
	s_nop 1
	v_addc_co_u32_e32 v33, vcc, 0, v3, vcc
	v_add_co_u32_e32 v34, vcc, s25, v2
	s_nop 1
	v_addc_co_u32_e32 v35, vcc, 0, v3, vcc
	global_load_dword v38, v[2:3], off nt
	global_load_dword v39, v[4:5], off offset:2048 nt
	global_load_dword v40, v[6:7], off nt
	global_load_dword v41, v[8:9], off offset:2048 nt
	global_load_dword v42, v[28:29], off nt
	global_load_dword v43, v[30:31], off offset:2048 nt
	global_load_dword v44, v[32:33], off nt
	global_load_dword v45, v[34:35], off offset:2048 nt
	v_add_co_u32_e32 v4, vcc, s26, v2
	s_nop 1
	v_addc_co_u32_e32 v5, vcc, 0, v3, vcc
	v_add_co_u32_e32 v6, vcc, s27, v2
	s_nop 1
	v_addc_co_u32_e32 v7, vcc, 0, v3, vcc
	v_add_co_u32_e32 v8, vcc, s28, v2
	s_nop 1
	v_addc_co_u32_e32 v9, vcc, 0, v3, vcc
	v_add_co_u32_e32 v28, vcc, s29, v2
	s_nop 1
	v_addc_co_u32_e32 v29, vcc, 0, v3, vcc
	v_add_co_u32_e32 v30, vcc, s30, v2
	s_nop 1
	v_addc_co_u32_e32 v31, vcc, 0, v3, vcc
	v_add_co_u32_e32 v32, vcc, s31, v2
	s_nop 1
	v_addc_co_u32_e32 v33, vcc, 0, v3, vcc
	v_add_co_u32_e32 v34, vcc, s33, v2
	s_nop 1
	v_addc_co_u32_e32 v35, vcc, 0, v3, vcc
	v_add_co_u32_e32 v36, vcc, s34, v2
	s_nop 1
	v_addc_co_u32_e32 v37, vcc, 0, v3, vcc
	global_load_dword v46, v[4:5], off nt
	global_load_dword v47, v[6:7], off offset:2048 nt
	global_load_dword v48, v[8:9], off nt
	global_load_dword v49, v[28:29], off offset:2048 nt
	global_load_dword v50, v[30:31], off nt
	global_load_dword v51, v[32:33], off offset:2048 nt
	global_load_dword v52, v[34:35], off nt
	global_load_dword v53, v[36:37], off offset:2048 nt
	v_add_co_u32_e32 v4, vcc, s35, v2
	s_nop 1
	v_addc_co_u32_e32 v5, vcc, 0, v3, vcc
	v_add_co_u32_e32 v6, vcc, s36, v2
	s_nop 1
	v_addc_co_u32_e32 v7, vcc, 0, v3, vcc
	v_add_co_u32_e32 v8, vcc, s37, v2
	s_nop 1
	v_addc_co_u32_e32 v9, vcc, 0, v3, vcc
	v_add_co_u32_e32 v28, vcc, s38, v2
	s_nop 1
	v_addc_co_u32_e32 v29, vcc, 0, v3, vcc
	v_add_co_u32_e32 v30, vcc, s39, v2
	s_nop 1
	v_addc_co_u32_e32 v31, vcc, 0, v3, vcc
	v_add_co_u32_e32 v32, vcc, s40, v2
	s_nop 1
	v_addc_co_u32_e32 v33, vcc, 0, v3, vcc
	v_add_co_u32_e32 v34, vcc, s41, v2
	s_nop 1
	v_addc_co_u32_e32 v35, vcc, 0, v3, vcc
	v_add_co_u32_e32 v36, vcc, s42, v2
	s_nop 1
	v_addc_co_u32_e32 v37, vcc, 0, v3, vcc
	global_load_dword v54, v[4:5], off nt
	global_load_dword v55, v[6:7], off offset:2048 nt
	global_load_dword v56, v[8:9], off nt
	global_load_dword v57, v[28:29], off offset:2048 nt
	global_load_dword v58, v[30:31], off nt
	global_load_dword v59, v[32:33], off offset:2048 nt
	global_load_dword v60, v[34:35], off nt
	s_nop 0
	global_load_dword v36, v[36:37], off offset:2048 nt
	v_add_co_u32_e32 v4, vcc, s43, v2
	s_nop 1
	v_addc_co_u32_e32 v5, vcc, 0, v3, vcc
	v_add_co_u32_e32 v6, vcc, s44, v2
	s_nop 1
	v_addc_co_u32_e32 v7, vcc, 0, v3, vcc
	v_add_co_u32_e32 v8, vcc, s45, v2
	s_nop 1
	v_addc_co_u32_e32 v9, vcc, 0, v3, vcc
	v_add_co_u32_e32 v28, vcc, s46, v2
	s_nop 1
	v_addc_co_u32_e32 v29, vcc, 0, v3, vcc
	v_add_co_u32_e32 v30, vcc, s47, v2
	s_nop 1
	v_addc_co_u32_e32 v31, vcc, 0, v3, vcc
	v_add_co_u32_e32 v32, vcc, s52, v2
	s_nop 1
	v_addc_co_u32_e32 v33, vcc, 0, v3, vcc
	v_add_co_u32_e32 v34, vcc, s53, v2
	s_nop 1
	v_addc_co_u32_e32 v35, vcc, 0, v3, vcc
	v_add_co_u32_e32 v2, vcc, s54, v2
	s_nop 1
	v_addc_co_u32_e32 v3, vcc, 0, v3, vcc
	global_load_dword v4, v[4:5], off nt
	s_nop 0
	global_load_dword v5, v[6:7], off offset:2048 nt
	s_nop 0
	global_load_dword v6, v[8:9], off nt
	global_load_dword v7, v[28:29], off offset:2048 nt
	s_nop 0
	global_load_dword v8, v[30:31], off nt
	global_load_dword v9, v[32:33], off offset:2048 nt
	global_load_dword v28, v[34:35], off nt
	s_nop 0
	global_load_dword v2, v[2:3], off offset:2048 nt
	s_waitcnt vmcnt(0)
	ds_write2_b32 v19, v38, v39 offset1:66
	ds_write2_b32 v19, v40, v41 offset0:132 offset1:198
	ds_write2_b32 v20, v42, v43 offset0:8 offset1:74
	ds_write2_b32 v20, v44, v45 offset0:140 offset1:206
	ds_write2_b32 v21, v46, v47 offset0:16 offset1:82
	ds_write2_b32 v21, v48, v49 offset0:148 offset1:214
	ds_write2_b32 v22, v50, v51 offset0:24 offset1:90
	ds_write2_b32 v22, v52, v53 offset0:156 offset1:222
	ds_write2_b32 v23, v54, v55 offset0:32 offset1:98
	ds_write2_b32 v23, v56, v57 offset0:164 offset1:230
	ds_write2_b32 v24, v58, v59 offset0:40 offset1:106
	ds_write2_b32 v24, v60, v36 offset0:172 offset1:238
	ds_write2_b32 v25, v4, v5 offset0:48 offset1:114
	ds_write2_b32 v25, v6, v7 offset0:180 offset1:246
	ds_write2_b32 v26, v8, v9 offset0:56 offset1:122
	ds_write2_b32 v26, v28, v2 offset0:188 offset1:254
	s_waitcnt lgkmcnt(0)
	s_cbranch_scc1 .LBB0_126
	s_lshl_b32 s15, s10, 2
	s_add_u32 s58, s12, s15
	s_addc_u32 s59, s13, 0
	global_load_dwordx4 v[2:5], v27, s[58:59] offset:16
	global_load_dwordx4 v[6:9], v27, s[58:59]
	s_branch .LBB0_127

; #define LAS __attribute__((address_space(3)))
; #define LDS_WAIT() asm volatile("s_waitcnt lgkmcnt(0)" ::: "memory")
; __device__ __forceinline__ void p0_transpose_item(const float* W, int K, int N, bf16* WT, int mode, LAS float* scr, int item, int lane, const float* kscale = nullptr) {
;     const int nblk = N / 32, kb = item / nblk, nb = item % nblk, k0 = 64 * kb, n0 = 32 * nb;
;     const int rb = (mode == 0 || mode == 3 || mode == 4) ? n0 : ((n0 >> 7) * 256 + (n0 & 127) + (mode == 2 ? 128 : 0));
;     float wv[32];
; #pragma unroll
;     for (int i = 0; i < 32; ++i) wv[i] = W[(size_t)(k0 + 2 * i + (lane >> 5)) * N + n0 + (lane & 31)];
; #pragma unroll
;     for (int i = 0; i < 32; ++i) scr[(2 * i + (lane >> 5)) * 33 + (lane & 31)] = wv[i];
;     LDS_WAIT(); asm volatile("" ::: "memory");
;     const int c = lane & 7;
;     f32x4 ks0 = (f32x4){1.f, 1.f, 1.f, 1.f}, ks1 = ks0; if (kscale) { ks0 = *(const f32x4*)(kscale + k0 + 8 * c); ks1 = *(const f32x4*)(kscale + k0 + 8 * c + 4); }
; template <int WHICH> __device__ __forceinline__ void convert_weights_dyn(const Frame& F, gu32* ctr) {
;     LAS float* scr = (LAS float*)(F.lds + RING_OFF + F.wave * 16384);
;     constexpr int NIT = WHICH == 3 ? 2 * I_3 : I_4;
;     for (;;) {
;         unsigned v = 0u; if (F.lane == 0) v = __hip_atomic_fetch_add(ctr, 8u, RLX_AGENT);
;         const int it0 = (int)__builtin_amdgcn_readfirstlane(v); if (it0 >= NIT) break;
; #pragma unroll 1
;         for (int k = 0; k < 8; ++k) { const int it = it0 + k; if (it >= NIT) break;
;             if (WHICH == 3) { if (it < I_3) p0_transpose_item(P_w_gate, DM, DFF, P_W3, 1, scr, it, F.lane, P_ffn_nw); else p0_transpose_item(P_w_up, DM, DFF, P_W3, 2, scr, it - I_3, F.lane, P_ffn_nw); }
;             else p0_transpose_item(P_w_down, DFF, DM, P_W4, 0, scr, it, F.lane); }
.LBB0_128:
	s_and_b64 vcc, exec, s[14:15]
	s_cbranch_vccz .LBB0_120
	s_mul_hi_i32 s10, s16, 0x2fa0be83
	s_lshr_b32 s14, s10, 31
	s_ashr_i32 s10, s10, 6
	s_add_i32 s14, s10, s14
	s_load_dwordx2 s[58:59], s[0:1], 0xa8
	s_mul_i32 s10, s14, 0x158
	s_sub_i32 s10, s16, s10
	s_lshl_b32 s16, s10, 5
	s_ashr_i32 s17, s16, 31
	s_lshl_b32 s14, s14, 6
	s_lshl_b64 s[62:63], s[16:17], 2
	s_waitcnt lgkmcnt(0)
	s_add_u32 s58, s58, s62
	v_or_b32_e32 v38, s14, v1
	s_addc_u32 s59, s59, s63
	v_lshl_add_u64 v[2:3], s[58:59], 0, v[10:11]
	v_or_b32_e32 v6, 2, v38
	v_or_b32_e32 v8, 4, v38
	v_or_b32_e32 v28, 6, v38
	v_or_b32_e32 v30, 8, v38
	v_or_b32_e32 v32, 10, v38
	v_or_b32_e32 v34, 12, v38
	v_or_b32_e32 v36, 14, v38
	v_mad_i64_i32 v[4:5], s[58:59], v38, s18, v[2:3]
	v_mad_i64_i32 v[6:7], s[58:59], v6, s18, v[2:3]
	v_mad_i64_i32 v[8:9], s[58:59], v8, s18, v[2:3]
	v_mad_i64_i32 v[28:29], s[58:59], v28, s18, v[2:3]
	v_mad_i64_i32 v[30:31], s[58:59], v30, s18, v[2:3]
	v_mad_i64_i32 v[32:33], s[58:59], v32, s18, v[2:3]
	v_mad_i64_i32 v[34:35], s[58:59], v34, s18, v[2:3]
	v_mad_i64_i32 v[36:37], s[58:59], v36, s18, v[2:3]
	global_load_dword v39, v[4:5], off nt
	global_load_dword v40, v[6:7], off nt
	global_load_dword v41, v[8:9], off nt
	global_load_dword v42, v[28:29], off nt
	global_load_dword v43, v[30:31], off nt
	global_load_dword v44, v[32:33], off nt
	global_load_dword v45, v[34:35], off nt
	global_load_dword v46, v[36:37], off nt
	v_or_b32_e32 v4, 16, v38
	v_or_b32_e32 v6, 18, v38
	v_or_b32_e32 v8, 20, v38
	v_or_b32_e32 v28, 22, v38
	v_or_b32_e32 v30, 24, v38
	v_or_b32_e32 v32, 26, v38
	v_or_b32_e32 v34, 28, v38
	v_or_b32_e32 v36, 30, v38
	v_mad_i64_i32 v[4:5], s[58:59], v4, s18, v[2:3]
	v_mad_i64_i32 v[6:7], s[58:59], v6, s18, v[2:3]
	v_mad_i64_i32 v[8:9], s[58:59], v8, s18, v[2:3]
	v_mad_i64_i32 v[28:29], s[58:59], v28, s18, v[2:3]
	v_mad_i64_i32 v[30:31], s[58:59], v30, s18, v[2:3]
	v_mad_i64_i32 v[32:33], s[58:59], v32, s18, v[2:3]
	v_mad_i64_i32 v[34:35], s[58:59], v34, s18, v[2:3]
	v_mad_i64_i32 v[36:37], s[58:59], v36, s18, v[2:3]
	global_load_dword v47, v[4:5], off nt
	global_load_dword v48, v[6:7], off nt
	global_load_dword v49, v[8:9], off nt
	global_load_dword v50, v[28:29], off nt
	global_load_dword v51, v[30:31], off nt
	global_load_dword v52, v[32:33], off nt
	global_load_dword v53, v[34:35], off nt
	global_load_dword v54, v[36:37], off nt
	v_or_b32_e32 v4, 32, v38
	v_or_b32_e32 v6, 34, v38
	v_or_b32_e32 v8, 36, v38
	v_or_b32_e32 v28, 38, v38
	v_or_b32_e32 v30, 40, v38
	v_or_b32_e32 v32, 42, v38
	v_or_b32_e32 v34, 44, v38
	v_or_b32_e32 v36, 46, v38
	v_mad_i64_i32 v[4:5], s[58:59], v4, s18, v[2:3]
	v_mad_i64_i32 v[6:7], s[58:59], v6, s18, v[2:3]
	v_mad_i64_i32 v[8:9], s[58:59], v8, s18, v[2:3]
	v_mad_i64_i32 v[28:29], s[58:59], v28, s18, v[2:3]
	v_mad_i64_i32 v[30:31], s[58:59], v30, s18, v[2:3]
	v_mad_i64_i32 v[32:33], s[58:59], v32, s18, v[2:3]
	v_mad_i64_i32 v[34:35], s[58:59], v34, s18, v[2:3]
	v_mad_i64_i32 v[36:37], s[58:59], v36, s18, v[2:3]
	global_load_dword v55, v[4:5], off nt
	global_load_dword v56, v[6:7], off nt
	global_load_dword v57, v[8:9], off nt
	global_load_dword v58, v[28:29], off nt
	global_load_dword v59, v[30:31], off nt
	global_load_dword v60, v[32:33], off nt
	global_load_dword v61, v[34:35], off nt
	s_nop 0
	global_load_dword v36, v[36:37], off nt
	v_or_b32_e32 v4, 48, v38
	v_or_b32_e32 v6, 50, v38
	v_or_b32_e32 v8, 52, v38
	v_or_b32_e32 v28, 54, v38
	v_or_b32_e32 v30, 56, v38
	v_or_b32_e32 v32, 58, v38
	v_or_b32_e32 v34, 60, v38
	v_or_b32_e32 v37, 62, v38
	v_mad_i64_i32 v[4:5], s[58:59], v4, s18, v[2:3]
	v_mad_i64_i32 v[6:7], s[58:59], v6, s18, v[2:3]
	v_mad_i64_i32 v[8:9], s[58:59], v8, s18, v[2:3]
	v_mad_i64_i32 v[28:29], s[58:59], v28, s18, v[2:3]
	v_mad_i64_i32 v[30:31], s[58:59], v30, s18, v[2:3]
	v_mad_i64_i32 v[32:33], s[58:59], v32, s18, v[2:3]
	v_mad_i64_i32 v[34:35], s[58:59], v34, s18, v[2:3]
	v_mad_i64_i32 v[2:3], s[58:59], v37, s18, v[2:3]
	global_load_dword v4, v[4:5], off nt
	s_nop 0
	global_load_dword v5, v[6:7], off nt
	s_nop 0
	global_load_dword v6, v[8:9], off nt
	global_load_dword v7, v[28:29], off nt
	s_nop 0
	global_load_dword v8, v[30:31], off nt
	global_load_dword v9, v[32:33], off nt
	global_load_dword v28, v[34:35], off nt
	s_nop 0
	global_load_dword v2, v[2:3], off nt
	s_waitcnt vmcnt(0)
	ds_write2_b32 v19, v39, v40 offset1:66
	ds_write2_b32 v19, v41, v42 offset0:132 offset1:198
	ds_write2_b32 v20, v43, v44 offset0:8 offset1:74
	ds_write2_b32 v20, v45, v46 offset0:140 offset1:206
	ds_write2_b32 v21, v47, v48 offset0:16 offset1:82
	ds_write2_b32 v21, v49, v50 offset0:148 offset1:214
	ds_write2_b32 v22, v51, v52 offset0:24 offset1:90
	ds_write2_b32 v22, v53, v54 offset0:156 offset1:222
	ds_write2_b32 v23, v55, v56 offset0:32 offset1:98
	ds_write2_b32 v23, v57, v58 offset0:164 offset1:230
	ds_write2_b32 v24, v59, v60 offset0:40 offset1:106
	ds_write2_b32 v24, v61, v36 offset0:172 offset1:238
	ds_write2_b32 v25, v4, v5 offset0:48 offset1:114
	ds_write2_b32 v25, v6, v7 offset0:180 offset1:246
	ds_write2_b32 v26, v8, v9 offset0:56 offset1:122
	ds_write2_b32 v26, v28, v2 offset0:188 offset1:254
	s_waitcnt lgkmcnt(0)
	s_ashr_i32 s15, s14, 31
	s_cmp_eq_u64 s[12:13], 0
	s_cbranch_scc0 .LBB0_118
	v_mov_b32_e32 v2, 1.0
	v_mov_b32_e32 v3, v2
	v_mov_b32_e32 v4, v2
	v_mov_b32_e32 v5, v2
	v_mov_b32_e32 v6, v2
	v_mov_b32_e32 v7, v2
	v_mov_b32_e32 v8, v2
	v_mov_b32_e32 v9, v2
	s_branch .LBB0_119

; #define LAS __attribute__((address_space(3)))
; __device__ __forceinline__ void unpack8(const u32x4 w, float (&f)[8]) { f[0] = bflo(w.x); f[1] = bfhi(w.x); f[2] = bflo(w.y); f[3] = bfhi(w.y); f[4] = bflo(w.z); f[5] = bfhi(w.z); f[6] = bflo(w.w); f[7] = bfhi(w.w); }
; __device__ __forceinline__ void attn_sample_unit(const Frame& F, const Ptrs& P, int unit) {
;     const int kvh = unit & 3, b = unit >> 2;
;     LAS unsigned char* Kl = F.lds + RING_OFF; LAS unsigned char* Vl = Kl + 160 * KS;
;     f32x4 ld[5][4];
; #pragma unroll
;     for (int it = 0; it < 5; ++it) { const int task = F.tid + 512 * it, r = task >> 4, ch = task & 15;
; #pragma unroll
;         for (int j = 0; j < 4; ++j) ld[it][j] = (f32x4){0.f, 0.f, 0.f, 0.f};
;         if (r < 128) { const size_t o = (((size_t)b * 128 + r) * 4 + kvh) * 128 + ch * 8;
;             ld[it][0] = *(const f32x4*)(P_st_k + o); ld[it][1] = *(const f32x4*)(P_st_k + o + 4); ld[it][2] = *(const f32x4*)(P_st_v + o); ld[it][3] = *(const f32x4*)(P_st_v + o + 4); }
;         else if (r < 136) { const bf16* pr = P_PROJ + (size_t)(MP + b * 8 + (r - 128)) * LDP + kvh * 128 + ch * 8; float kf[8], vf[8]; unpack8(*(const u32x4*)(pr + C_K), kf); unpack8(*(const u32x4*)(pr + C_V), vf);
;             ld[it][0] = (f32x4){kf[0], kf[1], kf[2], kf[3]}; ld[it][1] = (f32x4){kf[4], kf[5], kf[6], kf[7]}; ld[it][2] = (f32x4){vf[0], vf[1], vf[2], vf[3]}; ld[it][3] = (f32x4){vf[4], vf[5], vf[6], vf[7]}; } }
.LBB0_356:
	s_or_b64 exec, exec, s[20:21]
	s_ashr_i32 s30, s26, 2
	s_ashr_i32 s31, s30, 31
	s_and_b32 s62, s26, 3
	s_lshl_b64 s[34:35], s[30:31], 16
	s_load_dwordx4 s[20:23], s[0:1], 0x10
	s_lshl_b32 s64, s62, 7
	v_or_b32_e32 v2, s34, v100
	v_or_b32_e32 v2, s64, v2
	v_mov_b32_e32 v3, s35
	v_or_b32_e32 v2, v2, v96
	v_lshlrev_b64 v[2:3], 2, v[2:3]
	s_waitcnt lgkmcnt(0)
	v_lshl_add_u64 v[4:5], s[20:21], 0, v[2:3]
	v_lshl_add_u64 v[2:3], s[22:23], 0, v[2:3]
	global_load_dwordx4 v[86:89], v[4:5], off offset:16 nt
	global_load_dwordx4 v[90:93], v[4:5], off nt
	global_load_dwordx4 v[74:77], v[2:3], off offset:16 nt
	global_load_dwordx4 v[78:81], v[2:3], off nt
	v_or_b32_e32 v2, s34, v102
	v_or_b32_e32 v2, s64, v2
	v_mov_b32_e32 v3, s35
	v_or_b32_e32 v2, v2, v96
	v_lshlrev_b64 v[2:3], 2, v[2:3]
	v_lshl_add_u64 v[4:5], s[20:21], 0, v[2:3]
	v_lshl_add_u64 v[2:3], s[22:23], 0, v[2:3]
	global_load_dwordx4 v[62:65], v[4:5], off offset:16 nt
	global_load_dwordx4 v[70:73], v[4:5], off nt
	global_load_dwordx4 v[54:57], v[2:3], off offset:16 nt
	global_load_dwordx4 v[58:61], v[2:3], off nt
	v_or_b32_e32 v2, s34, v104
	v_or_b32_e32 v2, s64, v2
	v_mov_b32_e32 v3, s35
	v_or_b32_e32 v2, v2, v96
	v_lshlrev_b64 v[2:3], 2, v[2:3]
	v_lshl_add_u64 v[4:5], s[20:21], 0, v[2:3]
	v_lshl_add_u64 v[2:3], s[22:23], 0, v[2:3]
	global_load_dwordx4 v[42:45], v[4:5], off offset:16 nt
	global_load_dwordx4 v[46:49], v[4:5], off nt
	global_load_dwordx4 v[34:37], v[2:3], off offset:16 nt
	global_load_dwordx4 v[38:41], v[2:3], off nt
	s_lshl_b32 s63, s30, 3
	s_add_i32 s65, s63, 0x1f80
	s_and_saveexec_b64 s[36:37], s[4:5]
	s_xor_b64 s[36:37], exec, s[36:37]
	s_cbranch_execz .LBB0_360
	v_mov_b32_e32 v5, 0
	v_mov_b32_e32 v4, 0
	v_mov_b32_e32 v3, 0
	v_mov_b32_e32 v2, 0
	v_mov_b32_e32 v9, 0
	v_mov_b32_e32 v8, 0
	v_mov_b32_e32 v7, 0
	v_mov_b32_e32 v6, 0
	v_mov_b32_e32 v13, 0
	v_mov_b32_e32 v12, 0
	v_mov_b32_e32 v11, 0
	v_mov_b32_e32 v10, 0
	v_mov_b32_e32 v17, 0
	v_mov_b32_e32 v16, 0
	v_mov_b32_e32 v15, 0
	v_mov_b32_e32 v14, 0
	s_and_saveexec_b64 s[38:39], s[6:7]
	s_cbranch_execz .LBB0_359
	v_add_u32_e32 v4, s65, v1
	v_mov_b64_e32 v[2:3], s[46:47]
	v_mad_i64_i32 v[2:3], s[68:69], v4, s43, v[2:3]
	s_lshl_b32 s26, s64, 1
	v_lshl_add_u64 v[2:3], v[2:3], 0, s[26:27]
	v_lshlrev_b32_e32 v4, 1, v96
	v_mov_b32_e32 v5, v82
	v_lshl_add_u64 v[2:3], v[2:3], 0, v[4:5]
	v_add_co_u32_e32 v2, vcc, 0x1000, v2
	s_nop 1
	v_addc_co_u32_e32 v3, vcc, 0, v3, vcc
	global_load_dwordx4 v[6:9], v[2:3], off
	global_load_dwordx4 v[14:17], v[2:3], off offset:1024
	s_waitcnt vmcnt(1)
	v_lshlrev_b32_e32 v2, 16, v6
	v_and_b32_e32 v3, 0xffff0000, v6
	v_lshlrev_b32_e32 v4, 16, v7
	v_and_b32_e32 v5, 0xffff0000, v7
	v_lshlrev_b32_e32 v6, 16, v8
	v_and_b32_e32 v7, 0xffff0000, v8
	v_lshlrev_b32_e32 v8, 16, v9
	v_and_b32_e32 v9, 0xffff0000, v9
	s_waitcnt vmcnt(0)
	v_lshlrev_b32_e32 v10, 16, v14
	v_and_b32_e32 v11, 0xffff0000, v14
	v_lshlrev_b32_e32 v12, 16, v15
	v_and_b32_e32 v13, 0xffff0000, v15
	v_lshlrev_b32_e32 v14, 16, v16
	v_and_b32_e32 v15, 0xffff0000, v16
	v_lshlrev_b32_e32 v16, 16, v17
	v_and_b32_e32 v17, 0xffff0000, v17

; __device__ __forceinline__ void attn_sample_unit(const Frame& F, const Ptrs& P, int unit) {
;     ...
;     for (int it = 0; it < 5; ++it) { const int task = F.tid + 512 * it, r = task >> 4, ch = task & 15;
; #pragma unroll
;         for (int j = 0; j < 4; ++j) ld[it][j] = (f32x4){0.f, 0.f, 0.f, 0.f};
;         if (r < 128) { const size_t o = (((size_t)b * 128 + r) * 4 + kvh) * 128 + ch * 8;
;             ld[it][0] = *(const f32x4*)(P_st_k + o); ld[it][1] = *(const f32x4*)(P_st_k + o + 4); ld[it][2] = *(const f32x4*)(P_st_v + o); ld[it][3] = *(const f32x4*)(P_st_v + o + 4); }
.LBB0_360:
	s_andn2_saveexec_b64 s[36:37], s[36:37]
	s_cbranch_execz .LBB0_362
	v_or_b32_e32 v2, s34, v106
	v_or3_b32 v3, s35, 0, 0
	v_or3_b32 v2, v2, s64, v96
	v_lshlrev_b64 v[10:11], 2, v[2:3]
	v_lshl_add_u64 v[2:3], s[20:21], 0, v[10:11]
	v_lshl_add_u64 v[10:11], s[22:23], 0, v[10:11]
	global_load_dwordx4 v[6:9], v[2:3], off offset:16 nt
	s_nop 0
	global_load_dwordx4 v[2:5], v[2:3], off nt
	s_nop 0
	global_load_dwordx4 v[14:17], v[10:11], off offset:16 nt
	s_nop 0
	global_load_dwordx4 v[10:13], v[10:11], off nt

; #define LAS __attribute__((address_space(3)))
; #define STAMP(i) do { if (F.bid == PROBE_BID && F.tid == 0 && ((i) == PROBE_A || (i) == PROBE_B)) { const unsigned long long t_ = __builtin_amdgcn_s_memrealtime(); volatile LAS unsigned* m_ = (volatile LAS unsigned*)(F.lds + MISC_OFF) + ((i) == PROBE_A ? 16 : 18); m_[0] = (unsigned)t_; m_[1] = (unsigned)(t_ >> 32); } } while (0)
; #define STAMP(i) do { } while (0)
; __device__ __forceinline__ void ssd_sample_unit(const Frame& F, const Ptrs& P, int unit) {
;     const int grp = unit & 7, b = unit >> 3;
;     STAMP(40);
;     LAS float* XC = (LAS float*)(F.lds + RING_OFF); LAS float* BC = XC + 2048; LAS float* CC = BC + 1024; LAS float* ZC = CC + 1024; LAS float* DTVs = ZC + 2048; LAS float* ACSs = DTVs + 32;
;     LAS float* SQL = ACSs + 32; LAS float* CBm = SQL + 32; LAS float* Gm = CBm + 64; LAS float* Wm = Gm + 256; LAS float* Em = Wm + 32;
;     const int hh = F.wave >> 1, half = F.wave & 1, h = grp * 4 + hh, pl = F.lane & 31, hi = F.lane >> 5, p = 32 * half + pl;
;     const size_t sofs = ((size_t)(b * 32 + h) * 64 + p) * 128 + 8 * hi;
;     f32x4 hk[8][2];
; #pragma unroll
;     for (int ks = 0; ks < 8; ++ks) { hk[ks][0] = *(const f32x4*)(P_st_ssm + sofs + 16 * ks); hk[ks][1] = *(const f32x4*)(P_st_ssm + sofs + 16 * ks + 4); }
;     if (F.tid < 8) SQL[F.tid] = 0.f;
;     {   const int ci = F.tid; int ch, stride; LAS float* dst; const bf16* XB = (const bf16*)(P_ws + WS_XBCC);
;         if (ci < 256) { ch = grp * 256 + ci; dst = XC + ci; stride = 256; } else if (ci < 384) { ch = 2048 + grp * 128 + (ci - 256); dst = BC + (ci - 256); stride = 128; } else { ch = 3072 + grp * 128 + (ci - 384); dst = CC + (ci - 384); stride = 128; }
.LBB0_388:
	s_or_b64 exec, exec, s[70:71]
	s_and_b32 s66, s76, 7
	s_lshl_b32 s97, s66, 2
	s_lshl_b32 s70, s76, 2
	s_add_i32 s96, s97, s90
	s_and_b32 s72, s70, 0xffffffe0
	s_load_dwordx2 s[70:71], s[0:1], 0x20
	s_add_i32 s72, s96, s72
	s_ashr_i32 s73, s72, 31
	s_lshl_b64 s[72:73], s[72:73], 13
	v_lshl_add_u64 v[100:101], v[86:87], 0, s[72:73]
	s_waitcnt lgkmcnt(0)
	v_lshl_add_u64 v[2:3], v[100:101], 2, s[70:71]
	global_load_dwordx4 v[74:77], v[2:3], off offset:16 nt
	global_load_dwordx4 v[78:81], v[2:3], off nt
	global_load_dwordx4 v[66:69], v[2:3], off offset:80 nt
	global_load_dwordx4 v[70:73], v[2:3], off offset:64 nt
	global_load_dwordx4 v[58:61], v[2:3], off offset:144 nt
	global_load_dwordx4 v[62:65], v[2:3], off offset:128 nt
	global_load_dwordx4 v[50:53], v[2:3], off offset:208 nt
	global_load_dwordx4 v[54:57], v[2:3], off offset:192 nt
	global_load_dwordx4 v[42:45], v[2:3], off offset:272 nt
	global_load_dwordx4 v[46:49], v[2:3], off offset:256 nt
	global_load_dwordx4 v[34:37], v[2:3], off offset:336 nt
	global_load_dwordx4 v[38:41], v[2:3], off offset:320 nt
	global_load_dwordx4 v[26:29], v[2:3], off offset:400 nt
	global_load_dwordx4 v[30:33], v[2:3], off offset:384 nt
	global_load_dwordx4 v[18:21], v[2:3], off offset:464 nt
	global_load_dwordx4 v[22:25], v[2:3], off offset:448 nt
	s_and_saveexec_b64 s[70:71], s[6:7]
	ds_write_b32 v110, v85 offset:24832
	s_or_b64 exec, exec, s[70:71]
	s_and_saveexec_b64 s[70:71], s[10:11]
	s_xor_b64 s[70:71], exec, s[70:71]
	s_cbranch_execz .LBB0_396
	s_lshl_b32 s74, s66, 7
	s_and_saveexec_b64 s[72:73], s[12:13]
	s_xor_b64 s[72:73], exec, s[72:73]
	v_add_u32_e32 v2, s74, v111
	s_or_saveexec_b64 s[72:73], s[72:73]
	v_mov_b32_e32 v4, v112
	s_xor_b64 exec, exec, s[72:73]
	v_add_u32_e32 v2, s74, v113
	v_mov_b32_e32 v4, v114
	s_or_b64 exec, exec, s[72:73]
	s_or_saveexec_b64 s[70:71], s[70:71]
	v_mov_b32_e32 v5, 0x80
	s_xor_b64 exec, exec, s[70:71]
	s_cbranch_execnz .LBB0_397
	s_branch .LBB0_398

; #define LAS __attribute__((address_space(3)))
; __device__ __forceinline__ void p0_transpose_item(const float* W, int K, int N, bf16* WT, int mode, LAS float* scr, int item, int lane, const float* kscale = nullptr) {
;     const int nblk = N / 32, kb = item / nblk, nb = item % nblk, k0 = 64 * kb, n0 = 32 * nb;
;     const int rb = (mode == 0 || mode == 3 || mode == 4) ? n0 : ((n0 >> 7) * 256 + (n0 & 127) + (mode == 2 ? 128 : 0));
;     float wv[32];
; #pragma unroll
;     for (int i = 0; i < 32; ++i) wv[i] = W[(size_t)(k0 + 2 * i + (lane >> 5)) * N + n0 + (lane & 31)];
; template <int WHICH> __device__ __forceinline__ void convert_weights_dyn(const Frame& F, gu32* ctr) {
;     LAS float* scr = (LAS float*)(F.lds + RING_OFF + F.wave * 16384);
;     constexpr int NIT = WHICH == 3 ? 2 * I_3 : I_4;
;     for (;;) {
;         unsigned v = 0u; if (F.lane == 0) v = __hip_atomic_fetch_add(ctr, 8u, RLX_AGENT);
;         const int it0 = (int)__builtin_amdgcn_readfirstlane(v); if (it0 >= NIT) break;
; #pragma unroll 1
;         for (int k = 0; k < 8; ++k) { const int it = it0 + k; if (it >= NIT) break;
;             if (WHICH == 3) { if (it < I_3) p0_transpose_item(P_w_gate, DM, DFF, P_W3, 1, scr, it, F.lane, P_ffn_nw); else p0_transpose_item(P_w_up, DM, DFF, P_W3, 2, scr, it - I_3, F.lane, P_ffn_nw); }
;             else p0_transpose_item(P_w_down, DFF, DM, P_W4, 0, scr, it, F.lane); }
.LBB0_922:
	s_add_i32 s10, s12, s13
	s_cmpk_gt_i32 s10, 0x55ff
	s_mov_b64 s[8:9], -1
	s_cbranch_scc1 .LBB0_921
	s_ashr_i32 s8, s10, 31
	s_lshr_b32 s8, s8, 25
	s_add_i32 s8, s10, s8
	s_load_dwordx2 s[16:17], s[0:1], 0xc8
	s_ashr_i32 s9, s8, 7
	s_and_b32 s8, s8, 0x7ffff80
	s_sub_i32 s8, s10, s8
	s_lshl_b32 s8, s8, 5
	s_lshl_b32 s10, s9, 6
	s_ashr_i32 s9, s8, 31
	s_lshl_b64 s[18:19], s[8:9], 2
	v_or_b32_e32 v6, s10, v1
	s_waitcnt lgkmcnt(0)
	s_add_u32 s16, s16, s18
	s_addc_u32 s17, s17, s19
	v_ashrrev_i32_e32 v7, 31, v6
	v_or_b32_e32 v26, 2, v6
	v_or_b32_e32 v28, 4, v6
	v_or_b32_e32 v30, 6, v6
	v_or_b32_e32 v32, 8, v6
	v_or_b32_e32 v34, 10, v6
	v_or_b32_e32 v36, 12, v6
	v_or_b32_e32 v38, 14, v6
	v_lshl_add_u64 v[8:9], s[16:17], 0, v[2:3]
	v_lshlrev_b64 v[24:25], 14, v[6:7]
	v_ashrrev_i32_e32 v27, 31, v26
	v_ashrrev_i32_e32 v29, 31, v28
	v_ashrrev_i32_e32 v31, 31, v30
	v_ashrrev_i32_e32 v33, 31, v32
	v_ashrrev_i32_e32 v35, 31, v34
	v_ashrrev_i32_e32 v37, 31, v36
	v_ashrrev_i32_e32 v39, 31, v38
	v_lshl_add_u64 v[24:25], v[8:9], 0, v[24:25]
	v_lshlrev_b64 v[26:27], 14, v[26:27]
	v_lshlrev_b64 v[28:29], 14, v[28:29]
	v_lshlrev_b64 v[30:31], 14, v[30:31]
	v_lshlrev_b64 v[32:33], 14, v[32:33]
	v_lshlrev_b64 v[34:35], 14, v[34:35]
	v_lshlrev_b64 v[36:37], 14, v[36:37]
	v_lshlrev_b64 v[38:39], 14, v[38:39]
	v_lshl_add_u64 v[26:27], v[8:9], 0, v[26:27]
	v_lshl_add_u64 v[28:29], v[8:9], 0, v[28:29]
	v_lshl_add_u64 v[30:31], v[8:9], 0, v[30:31]
	v_lshl_add_u64 v[32:33], v[8:9], 0, v[32:33]
	v_lshl_add_u64 v[34:35], v[8:9], 0, v[34:35]
	v_lshl_add_u64 v[36:37], v[8:9], 0, v[36:37]
	v_lshl_add_u64 v[38:39], v[8:9], 0, v[38:39]
	global_load_dword v23, v[24:25], off nt
	global_load_dword v40, v[26:27], off nt
	global_load_dword v41, v[28:29], off nt
	global_load_dword v42, v[30:31], off nt
	global_load_dword v43, v[32:33], off nt
	global_load_dword v44, v[34:35], off nt
	global_load_dword v45, v[36:37], off nt
	global_load_dword v46, v[38:39], off nt
	v_or_b32_e32 v24, 16, v6
	v_ashrrev_i32_e32 v25, 31, v24
	v_or_b32_e32 v26, 18, v6
	v_or_b32_e32 v28, 20, v6
	v_or_b32_e32 v30, 22, v6
	v_or_b32_e32 v32, 24, v6
	v_or_b32_e32 v34, 26, v6
	v_or_b32_e32 v36, 28, v6
	v_or_b32_e32 v38, 30, v6
	v_lshlrev_b64 v[24:25], 14, v[24:25]
	v_ashrrev_i32_e32 v27, 31, v26
	v_ashrrev_i32_e32 v29, 31, v28
	v_ashrrev_i32_e32 v31, 31, v30
	v_ashrrev_i32_e32 v33, 31, v32
	v_ashrrev_i32_e32 v35, 31, v34
	v_ashrrev_i32_e32 v37, 31, v36
	v_ashrrev_i32_e32 v39, 31, v38
	v_lshl_add_u64 v[24:25], v[8:9], 0, v[24:25]
	v_lshlrev_b64 v[26:27], 14, v[26:27]
	v_lshlrev_b64 v[28:29], 14, v[28:29]
	v_lshlrev_b64 v[30:31], 14, v[30:31]
	v_lshlrev_b64 v[32:33], 14, v[32:33]
	v_lshlrev_b64 v[34:35], 14, v[34:35]
	v_lshlrev_b64 v[36:37], 14, v[36:37]
	v_lshlrev_b64 v[38:39], 14, v[38:39]
	v_lshl_add_u64 v[26:27], v[8:9], 0, v[26:27]
	v_lshl_add_u64 v[28:29], v[8:9], 0, v[28:29]
	v_lshl_add_u64 v[30:31], v[8:9], 0, v[30:31]
	v_lshl_add_u64 v[32:33], v[8:9], 0, v[32:33]
	v_lshl_add_u64 v[34:35], v[8:9], 0, v[34:35]
	v_lshl_add_u64 v[36:37], v[8:9], 0, v[36:37]
	v_lshl_add_u64 v[38:39], v[8:9], 0, v[38:39]
	global_load_dword v47, v[24:25], off nt
	global_load_dword v48, v[26:27], off nt
	global_load_dword v49, v[28:29], off nt
	global_load_dword v50, v[30:31], off nt
	global_load_dword v51, v[32:33], off nt
	global_load_dword v52, v[34:35], off nt
	global_load_dword v53, v[36:37], off nt
	global_load_dword v54, v[38:39], off nt
	v_or_b32_e32 v24, 32, v6
	v_ashrrev_i32_e32 v25, 31, v24
	v_or_b32_e32 v26, 34, v6
	v_or_b32_e32 v28, 36, v6
	v_or_b32_e32 v30, 38, v6
	v_or_b32_e32 v32, 40, v6
	v_or_b32_e32 v34, 42, v6
	v_or_b32_e32 v36, 44, v6
	v_or_b32_e32 v38, 46, v6
	v_lshlrev_b64 v[24:25], 14, v[24:25]
	v_ashrrev_i32_e32 v27, 31, v26
	v_ashrrev_i32_e32 v29, 31, v28
	v_ashrrev_i32_e32 v31, 31, v30
	v_ashrrev_i32_e32 v33, 31, v32
	v_ashrrev_i32_e32 v35, 31, v34
	v_ashrrev_i32_e32 v37, 31, v36
	v_ashrrev_i32_e32 v39, 31, v38
	v_lshl_add_u64 v[24:25], v[8:9], 0, v[24:25]
	v_lshlrev_b64 v[26:27], 14, v[26:27]
	v_lshlrev_b64 v[28:29], 14, v[28:29]
	v_lshlrev_b64 v[30:31], 14, v[30:31]
	v_lshlrev_b64 v[32:33], 14, v[32:33]
	v_lshlrev_b64 v[34:35], 14, v[34:35]
	v_lshlrev_b64 v[36:37], 14, v[36:37]
	v_lshlrev_b64 v[38:39], 14, v[38:39]
	v_lshl_add_u64 v[26:27], v[8:9], 0, v[26:27]
	v_lshl_add_u64 v[28:29], v[8:9], 0, v[28:29]
	v_lshl_add_u64 v[30:31], v[8:9], 0, v[30:31]
	v_lshl_add_u64 v[32:33], v[8:9], 0, v[32:33]
	v_lshl_add_u64 v[34:35], v[8:9], 0, v[34:35]
	v_lshl_add_u64 v[36:37], v[8:9], 0, v[36:37]
	v_lshl_add_u64 v[38:39], v[8:9], 0, v[38:39]
	global_load_dword v55, v[24:25], off nt
	global_load_dword v56, v[26:27], off nt
	global_load_dword v57, v[28:29], off nt
	global_load_dword v58, v[30:31], off nt
	global_load_dword v59, v[32:33], off nt
	global_load_dword v60, v[34:35], off nt
	global_load_dword v61, v[36:37], off nt
	global_load_dword v62, v[38:39], off nt
	v_or_b32_e32 v24, 48, v6
	v_ashrrev_i32_e32 v25, 31, v24
	v_or_b32_e32 v26, 50, v6
	v_or_b32_e32 v28, 52, v6
	v_or_b32_e32 v30, 54, v6
	v_or_b32_e32 v32, 56, v6
	v_or_b32_e32 v34, 58, v6
	v_or_b32_e32 v36, 60, v6
	v_or_b32_e32 v6, 62, v6
	v_lshlrev_b64 v[24:25], 14, v[24:25]
	v_ashrrev_i32_e32 v27, 31, v26
	v_ashrrev_i32_e32 v29, 31, v28
	v_ashrrev_i32_e32 v31, 31, v30
	v_ashrrev_i32_e32 v33, 31, v32
	v_ashrrev_i32_e32 v35, 31, v34
	v_ashrrev_i32_e32 v37, 31, v36
	v_ashrrev_i32_e32 v7, 31, v6
	v_lshl_add_u64 v[24:25], v[8:9], 0, v[24:25]
	v_lshlrev_b64 v[26:27], 14, v[26:27]
	v_lshlrev_b64 v[28:29], 14, v[28:29]
	v_lshlrev_b64 v[30:31], 14, v[30:31]
	v_lshlrev_b64 v[32:33], 14, v[32:33]
	v_lshlrev_b64 v[34:35], 14, v[34:35]
	v_lshlrev_b64 v[36:37], 14, v[36:37]
	v_lshlrev_b64 v[6:7], 14, v[6:7]
	v_lshl_add_u64 v[26:27], v[8:9], 0, v[26:27]
	v_lshl_add_u64 v[28:29], v[8:9], 0, v[28:29]
	v_lshl_add_u64 v[30:31], v[8:9], 0, v[30:31]
	v_lshl_add_u64 v[32:33], v[8:9], 0, v[32:33]
	v_lshl_add_u64 v[34:35], v[8:9], 0, v[34:35]
	v_lshl_add_u64 v[36:37], v[8:9], 0, v[36:37]
	v_lshl_add_u64 v[6:7], v[8:9], 0, v[6:7]
	global_load_dword v8, v[24:25], off nt
	global_load_dword v9, v[26:27], off nt
	global_load_dword v38, v[28:29], off nt
	global_load_dword v39, v[30:31], off nt
	global_load_dword v63, v[32:33], off nt
	global_load_dword v64, v[34:35], off nt
	global_load_dword v65, v[36:37], off nt
	global_load_dword v66, v[6:7], off nt
	s_waitcnt vmcnt(0)
; #define LAS __attribute__((address_space(3)))
; #define LDS_WAIT() asm volatile("s_waitcnt lgkmcnt(0)" ::: "memory")
; __device__ __forceinline__ unsigned cvtpk(float lo, float hi) { f32x2_t v = {lo, hi}; bf16x2_t b = __builtin_convertvector(v, bf16x2_t); return __builtin_bit_cast(unsigned, b); }
; __device__ __forceinline__ void p0_transpose_item(const float* W, int K, int N, bf16* WT, int mode, LAS float* scr, int item, int lane, const float* kscale = nullptr) {
;     ...
;     for (int i = 0; i < 32; ++i) scr[(2 * i + (lane >> 5)) * 33 + (lane & 31)] = wv[i];
;     LDS_WAIT(); asm volatile("" ::: "memory");
;     const int c = lane & 7;
;     f32x4 ks0 = (f32x4){1.f, 1.f, 1.f, 1.f}, ks1 = ks0; if (kscale) { ks0 = *(const f32x4*)(kscale + k0 + 8 * c); ks1 = *(const f32x4*)(kscale + k0 + 8 * c + 4); }
; #pragma unroll
;     for (int j = 0; j < 4; ++j) { const int n = (lane >> 3) + 8 * j; const LAS float* s = scr + (8 * c) * 33 + n;
;         u32x4 o; o.x = cvtpk(s[0 * 33] * ks0.x, s[1 * 33] * ks0.y); o.y = cvtpk(s[2 * 33] * ks0.z, s[3 * 33] * ks0.w); o.z = cvtpk(s[4 * 33] * ks1.x, s[5 * 33] * ks1.y); o.w = cvtpk(s[6 * 33] * ks1.z, s[7 * 33] * ks1.w);
;         const int k0d = (mode == 4) ? ((k0 + 2048) & 4095) : k0;
;         const size_t dst = (mode == 3) ? ((size_t)(((rb + n) >> 8) * (K >> 6) + kb) * 256 + ((rb + n) & 255)) * 64 + 8 * c : (size_t)(rb + n) * K + k0d + 8 * c;
;         *(u32x4*)(WT + dst) = o; }
;     LDS_WAIT(); asm volatile("" ::: "memory");
; template <int WHICH> __device__ __forceinline__ void convert_weights_dyn(const Frame& F, gu32* ctr) {
;     ...
; #pragma unroll 1
;         for (int k = 0; k < 8; ++k) { const int it = it0 + k; if (it >= NIT) break;
;             if (WHICH == 3) { if (it < I_3) p0_transpose_item(P_w_gate, DM, DFF, P_W3, 1, scr, it, F.lane, P_ffn_nw); else p0_transpose_item(P_w_up, DM, DFF, P_W3, 2, scr, it - I_3, F.lane, P_ffn_nw); }
;             else p0_transpose_item(P_w_down, DFF, DM, P_W4, 0, scr, it, F.lane); }
	ds_write2_b32 v15, v23, v40 offset1:66
	ds_write2_b32 v15, v41, v42 offset0:132 offset1:198
	ds_write2_b32 v16, v43, v44 offset0:8 offset1:74
	ds_write2_b32 v16, v45, v46 offset0:140 offset1:206
	ds_write2_b32 v17, v47, v48 offset0:16 offset1:82
	ds_write2_b32 v17, v49, v50 offset0:148 offset1:214
	ds_write2_b32 v18, v51, v52 offset0:24 offset1:90
	ds_write2_b32 v18, v53, v54 offset0:156 offset1:222
	ds_write2_b32 v19, v55, v56 offset0:32 offset1:98
	ds_write2_b32 v19, v57, v58 offset0:164 offset1:230
	ds_write2_b32 v20, v59, v60 offset0:40 offset1:106
	ds_write2_b32 v20, v61, v62 offset0:172 offset1:238
	ds_write2_b32 v21, v8, v9 offset0:48 offset1:114
	ds_write2_b32 v21, v38, v39 offset0:180 offset1:246
	ds_write2_b32 v22, v63, v64 offset0:56 offset1:122
	ds_write2_b32 v22, v65, v66 offset0:188 offset1:254
	s_waitcnt lgkmcnt(0)
	ds_read2_b32 v[24:25], v11 offset0:33 offset1:41
	ds_read2_b32 v[26:27], v11 offset1:8
	ds_read2_b32 v[28:29], v11 offset0:66 offset1:74
	ds_read2_b32 v[30:31], v11 offset0:99 offset1:107
	ds_read2_b32 v[32:33], v11 offset0:132 offset1:140
	ds_read2_b32 v[34:35], v11 offset0:165 offset1:173
	ds_read2_b32 v[36:37], v11 offset0:198 offset1:206
	ds_read2_b32 v[38:39], v11 offset0:231 offset1:239
	v_or_b32_e32 v23, s8, v10
	s_ashr_i32 s11, s10, 31
	v_mul_lo_u32 v42, v23, s14
	v_lshl_add_u64 v[40:41], s[10:11], 1, v[4:5]
	v_ashrrev_i32_e32 v43, 31, v42
	s_waitcnt lgkmcnt(6)
	v_cvt_pk_bf16_f32 v6, v26, v24
	s_waitcnt lgkmcnt(4)
	v_cvt_pk_bf16_f32 v7, v28, v30
	s_waitcnt lgkmcnt(2)
	v_cvt_pk_bf16_f32 v8, v32, v34
	s_waitcnt lgkmcnt(0)
	v_cvt_pk_bf16_f32 v9, v36, v38
	v_lshl_add_u64 v[42:43], v[40:41], 0, v[42:43]
	global_store_dwordx4 v[42:43], v[6:9], off
	v_or_b32_e32 v23, s8, v12
	v_mul_lo_u32 v24, v23, s14
	v_cvt_pk_bf16_f32 v6, v27, v25
	v_cvt_pk_bf16_f32 v7, v29, v31
	v_cvt_pk_bf16_f32 v8, v33, v35
	v_cvt_pk_bf16_f32 v9, v37, v39
	ds_read2_b32 v[26:27], v11 offset0:49 offset1:57
	ds_read2_b32 v[28:29], v11 offset0:16 offset1:24
	ds_read2_b32 v[30:31], v11 offset0:82 offset1:90
	ds_read2_b32 v[32:33], v11 offset0:115 offset1:123
	ds_read2_b32 v[34:35], v11 offset0:148 offset1:156
	ds_read2_b32 v[36:37], v11 offset0:181 offset1:189
	ds_read2_b32 v[38:39], v11 offset0:214 offset1:222
	ds_read2_b32 v[42:43], v11 offset0:247 offset1:255
	v_ashrrev_i32_e32 v25, 31, v24
	v_lshl_add_u64 v[24:25], v[40:41], 0, v[24:25]
	v_or_b32_e32 v23, s8, v13
	global_store_dwordx4 v[24:25], v[6:9], off
	v_mul_lo_u32 v24, v23, s14
	v_ashrrev_i32_e32 v25, 31, v24
	s_waitcnt lgkmcnt(6)
	v_cvt_pk_bf16_f32 v6, v28, v26
	s_waitcnt lgkmcnt(4)
	v_cvt_pk_bf16_f32 v7, v30, v32
	s_waitcnt lgkmcnt(2)
	v_cvt_pk_bf16_f32 v8, v34, v36
	s_waitcnt lgkmcnt(0)
	v_cvt_pk_bf16_f32 v9, v38, v42
	v_lshl_add_u64 v[24:25], v[40:41], 0, v[24:25]
	v_or_b32_e32 v23, s8, v14
	global_store_dwordx4 v[24:25], v[6:9], off
	v_mul_lo_u32 v24, v23, s14
	v_ashrrev_i32_e32 v25, 31, v24
	v_cvt_pk_bf16_f32 v6, v29, v27
	v_cvt_pk_bf16_f32 v7, v31, v33
	v_cvt_pk_bf16_f32 v8, v35, v37
	v_cvt_pk_bf16_f32 v9, v39, v43
	v_lshl_add_u64 v[24:25], v[40:41], 0, v[24:25]
	global_store_dwordx4 v[24:25], v[6:9], off
	s_waitcnt lgkmcnt(0)
	s_add_i32 s13, s13, 1
	s_cmp_eq_u32 s13, 8
	s_cselect_b64 s[8:9], -1, 0
	s_branch .LBB0_921
